# v75 + U^T tiles of the in-proj epilogue: 4x4 token/channel transpose inside lane quads (DPP + v_perm) and one 8-byte store per lane instead of four 2-byte stores
# baseline (speedup 1.0000x reference)
.LBB0_1279:
	s_lshl_b32 s4, s44, 8
	v_mov_b32_e32 v2, v188
	v_mov_b32_e32 v226, v189
	s_add_i32 s4, s4, s95
	s_lshl_b32 s67, s80, 8
	v_add_u32_e32 v225, s4, v2
	s_cmp_gt_i32 s80, 10
	s_mov_b64 s[4:5], -1
	v_add_u32_e32 v224, 16, v225
	v_add_u32_e32 v223, 32, v225
	v_add_u32_e32 v222, 48, v225
	v_add_u32_e32 v221, 0x80, v225
	v_add_u32_e32 v220, 0x90, v225
	v_add_u32_e32 v195, 0xa0, v225
	v_add_u32_e32 v194, 0xb0, v225
	s_cbranch_scc1 .LBB0_1363
	s_cmp_gt_i32 s44, 15
	s_cselect_b64 s[76:77], -1, 0
	s_cmp_lt_i32 s44, 16
	s_cselect_b64 s[40:41], -1, 0
	v_lshlrev_b32_e32 v227, 2, v226
	v_readlane_b32 s4, v254, 62
	v_and_b32_e32 v2, 1, v226
	v_add_u32_e32 v132, 12, v227
	v_add_u32_e32 v233, s4, v227
	s_and_b64 s[4:5], s[40:41], exec
	s_movk_i32 s4, 0x3ff
	s_cselect_b32 s82, 0xff, s4
	s_cselect_b32 s68, 8, 10
	v_readlane_b32 s4, v255, 0
	v_cmp_eq_u32_e64 s[42:43], 0, v2
	s_cselect_b32 s65, 0, 0x200000
	s_lshl_b32 s64, 1, s68
	s_lshl_b32 s63, 2, s68
	s_lshl_b32 s62, 3, s68
	v_add_u32_e32 v232, s4, v227
	v_cndmask_b32_e64 v229, v132, v227, s[42:43]
	v_readlane_b32 s4, v255, 3
	s_cmp_gt_i32 s80, 2
	s_nop 0
	v_add_u32_e32 v228, s4, v229
	s_mov_b64 s[4:5], -1
	s_cbranch_scc0 .LBB0_1340
	s_cmpk_gt_u32 s67, 0x4ff
	s_cbranch_scc0 .LBB0_1337
	s_cmpk_gt_u32 s67, 0x6ff
	s_cbranch_scc0 .LBB0_1319
	s_cmpk_gt_u32 s67, 0x8ff
	s_cbranch_scc1 .Lts_fast0
	v_bfe_u32 v2, v128, 16, 1
	v_add3_u32 v2, v128, v2, s37
	v_lshrrev_b32_e32 v239, 16, v2
	v_bfe_u32 v2, v129, 16, 1
	v_add3_u32 v2, v129, v2, s37
	v_lshrrev_b32_e32 v238, 16, v2
	v_bfe_u32 v2, v130, 16, 1
	v_add3_u32 v2, v130, v2, s37
	v_lshrrev_b32_e32 v237, 16, v2
	v_bfe_u32 v2, v131, 16, 1
	v_add3_u32 v2, v131, v2, s37
	v_mov_b32_e32 v196, v202
	v_lshrrev_b32_e32 v236, 16, v2
	v_bfe_u32 v2, v112, 16, 1
	v_bfe_u32 v132, v113, 16, 1
	v_bfe_u32 v133, v114, 16, 1
	v_bfe_u32 v134, v115, 16, 1
	v_bfe_u32 v135, v96, 16, 1
	v_bfe_u32 v136, v97, 16, 1
	v_bfe_u32 v137, v98, 16, 1
	v_bfe_u32 v138, v99, 16, 1
	v_bfe_u32 v139, v80, 16, 1
	v_bfe_u32 v140, v81, 16, 1
	v_bfe_u32 v141, v82, 16, 1
	v_bfe_u32 v142, v83, 16, 1
	v_bfe_u32 v143, v64, 16, 1
	v_bfe_u32 v144, v65, 16, 1
	v_bfe_u32 v145, v66, 16, 1
	v_bfe_u32 v146, v67, 16, 1
	v_bfe_u32 v147, v48, 16, 1
	v_bfe_u32 v148, v49, 16, 1
	v_bfe_u32 v149, v50, 16, 1
	v_bfe_u32 v150, v51, 16, 1
	v_bfe_u32 v151, v32, 16, 1
	v_bfe_u32 v152, v33, 16, 1
	v_bfe_u32 v153, v34, 16, 1
	v_bfe_u32 v154, v35, 16, 1
	v_bfe_u32 v155, v16, 16, 1
	v_bfe_u32 v156, v17, 16, 1
	v_bfe_u32 v157, v18, 16, 1
	v_bfe_u32 v158, v19, 16, 1
	v_bfe_u32 v159, v124, 16, 1
	v_bfe_u32 v160, v125, 16, 1
	v_bfe_u32 v161, v126, 16, 1
	v_bfe_u32 v244, v127, 16, 1
	v_bfe_u32 v245, v108, 16, 1
	v_bfe_u32 v246, v109, 16, 1
	v_bfe_u32 v247, v110, 16, 1
	v_bfe_u32 v248, v111, 16, 1
	v_bfe_u32 v249, v92, 16, 1
	v_bfe_u32 v250, v93, 16, 1
	v_bfe_u32 v251, v94, 16, 1
	v_bfe_u32 v252, v95, 16, 1
	v_bfe_u32 v253, v76, 16, 1
	v_bfe_u32 v206, v77, 16, 1
	v_bfe_u32 v209, v78, 16, 1
	v_bfe_u32 v207, v79, 16, 1
	v_bfe_u32 v208, v60, 16, 1
	v_bfe_u32 v197, v61, 16, 1
	v_bfe_u32 v201, v62, 16, 1
	v_bfe_u32 v214, v63, 16, 1
	v_bfe_u32 v215, v44, 16, 1
	v_bfe_u32 v204, v45, 16, 1
	v_bfe_u32 v216, v46, 16, 1
	v_bfe_u32 v219, v47, 16, 1
	v_bfe_u32 v210, v28, 16, 1
	v_bfe_u32 v0, v29, 16, 1
	v_bfe_u32 v198, v30, 16, 1
	v_bfe_u32 v217, v31, 16, 1
	v_bfe_u32 v202, v12, 16, 1
	v_bfe_u32 v203, v13, 16, 1
	v_bfe_u32 v218, v14, 16, 1
	v_bfe_u32 v1, v15, 16, 1
	s_cmpk_gt_u32 s67, 0x8ff
	v_add3_u32 v243, v112, v2, s37
	v_add3_u32 v242, v113, v132, s37
	v_add3_u32 v241, v114, v133, s37
	v_add3_u32 v240, v115, v134, s37
	v_add3_u32 v235, v96, v135, s37
	v_add3_u32 v234, v97, v136, s37
	v_add3_u32 v231, v98, v137, s37
	v_add3_u32 v230, v99, v138, s37
	v_add3_u32 v187, v80, v139, s37
	v_add3_u32 v186, v81, v140, s37
	v_add3_u32 v185, v82, v141, s37
	v_add3_u32 v184, v83, v142, s37
	v_add3_u32 v179, v64, v143, s37
	v_add3_u32 v178, v65, v144, s37
	v_add3_u32 v177, v66, v145, s37
	v_add3_u32 v176, v67, v146, s37
	v_add3_u32 v175, v48, v147, s37
	v_add3_u32 v174, v49, v148, s37
	v_add3_u32 v173, v50, v149, s37
	v_add3_u32 v172, v51, v150, s37
	v_add3_u32 v171, v32, v151, s37
	v_add3_u32 v170, v33, v152, s37
	v_add3_u32 v169, v34, v153, s37
	v_add3_u32 v168, v35, v154, s37
	v_add3_u32 v167, v16, v155, s37
	v_add3_u32 v166, v17, v156, s37
	v_add3_u32 v165, v18, v157, s37
	v_add3_u32 v164, v19, v158, s37
	v_add3_u32 v163, v124, v159, s37
	v_add3_u32 v162, v125, v160, s37
	v_add3_u32 v161, v126, v161, s37
	v_add3_u32 v160, v127, v244, s37
	v_add3_u32 v159, v108, v245, s37
	v_add3_u32 v158, v109, v246, s37
	v_add3_u32 v157, v110, v247, s37
	v_add3_u32 v156, v111, v248, s37
	v_add3_u32 v155, v92, v249, s37
	v_add3_u32 v154, v93, v250, s37
	v_add3_u32 v153, v94, v251, s37
	v_add3_u32 v152, v95, v252, s37
	v_add3_u32 v151, v76, v253, s37
	v_add3_u32 v150, v77, v206, s37
	v_add3_u32 v149, v78, v209, s37
	v_add3_u32 v148, v79, v207, s37
	v_add3_u32 v147, v60, v208, s37
	v_add3_u32 v146, v61, v197, s37
	v_add3_u32 v145, v62, v201, s37
	v_add3_u32 v144, v63, v214, s37
	v_add3_u32 v143, v44, v215, s37
	v_add3_u32 v142, v45, v204, s37
	v_add3_u32 v141, v46, v216, s37
	v_add3_u32 v140, v47, v219, s37
	v_add3_u32 v139, v28, v210, s37
	v_add3_u32 v138, v29, v0, s37
	v_add3_u32 v137, v30, v198, s37
	v_add3_u32 v136, v31, v217, s37
	v_add3_u32 v135, v12, v202, s37
	v_add3_u32 v134, v13, v203, s37
	v_add3_u32 v133, v14, v218, s37
	v_add3_u32 v132, v15, v1, s37
	s_cbranch_scc0 .LBB0_1285
	v_mov_b32_e32 v1, v225
	v_add_u32_e32 v0, s67, v233
	v_add_u32_e32 v197, 0xfffff000, v1
	v_lshrrev_b32_e32 v2, 8, v1
	v_ashrrev_i32_e32 v197, 10, v197
	v_cndmask_b32_e64 v2, v197, v2, s[40:41]
	v_and_b32_e32 v1, s82, v1
	v_lshl_add_u32 v2, v2, 9, v0
	v_or_b32_e32 v1, s65, v1
	v_lshl_add_u32 v2, v2, s68, v1
	v_lshl_add_u64 v[244:245], v[2:3], 1, s[60:61]
	s_lshl_b32 s20, s64, 1
	v_lshl_add_u64 v[246:247], v[244:245], 0, s[20:21]
	s_lshl_b32 s4, s63, 1
	s_mov_b32 s5, s21
	s_lshl_b32 s44, s62, 1
	s_mov_b32 s45, s21
	global_store_short v[244:245], v239, off
	global_store_short v[246:247], v238, off
	v_lshl_add_u64 v[246:247], v[244:245], 0, s[4:5]
	v_lshl_add_u64 v[244:245], v[244:245], 0, s[44:45]
	v_mov_b32_e32 v1, v224
	global_store_short v[246:247], v237, off
	global_store_short v[244:245], v236, off
	s_nop 0
	v_add_u32_e32 v197, 0xfffff000, v1
	v_lshrrev_b32_e32 v2, 8, v1
	v_ashrrev_i32_e32 v197, 10, v197
	v_cndmask_b32_e64 v2, v197, v2, s[40:41]
	v_and_b32_e32 v1, s82, v1
	v_lshl_add_u32 v2, v2, 9, v0
	v_or_b32_e32 v1, s65, v1
	v_lshl_add_u32 v2, v2, s68, v1
	v_lshl_add_u64 v[244:245], v[2:3], 1, s[60:61]
	v_lshl_add_u64 v[246:247], v[244:245], 0, s[20:21]
	global_store_short_d16_hi v[244:245], v243, off
	global_store_short_d16_hi v[246:247], v242, off
	v_lshl_add_u64 v[246:247], v[244:245], 0, s[4:5]
	v_lshl_add_u64 v[244:245], v[244:245], 0, s[44:45]
	v_mov_b32_e32 v1, v223
	global_store_short_d16_hi v[246:247], v241, off
	global_store_short_d16_hi v[244:245], v240, off
	s_nop 0
	v_add_u32_e32 v197, 0xfffff000, v1
	v_lshrrev_b32_e32 v2, 8, v1
	v_ashrrev_i32_e32 v197, 10, v197
	v_cndmask_b32_e64 v2, v197, v2, s[40:41]
	v_and_b32_e32 v1, s82, v1
	v_lshl_add_u32 v2, v2, 9, v0
	v_or_b32_e32 v1, s65, v1
	v_lshl_add_u32 v2, v2, s68, v1
	v_lshl_add_u64 v[244:245], v[2:3], 1, s[60:61]
	v_lshl_add_u64 v[246:247], v[244:245], 0, s[20:21]
	global_store_short_d16_hi v[244:245], v235, off
	global_store_short_d16_hi v[246:247], v234, off
	v_lshl_add_u64 v[246:247], v[244:245], 0, s[4:5]
	v_lshl_add_u64 v[244:245], v[244:245], 0, s[44:45]
	v_mov_b32_e32 v1, v222
	global_store_short_d16_hi v[246:247], v231, off
	global_store_short_d16_hi v[244:245], v230, off
	s_nop 0
	v_add_u32_e32 v197, 0xfffff000, v1
	v_lshrrev_b32_e32 v2, 8, v1
	v_ashrrev_i32_e32 v197, 10, v197
	v_cndmask_b32_e64 v2, v197, v2, s[40:41]
	v_and_b32_e32 v1, s82, v1
	v_lshl_add_u32 v2, v2, 9, v0
	v_or_b32_e32 v1, s65, v1
	v_lshl_add_u32 v2, v2, s68, v1
	v_lshl_add_u64 v[244:245], v[2:3], 1, s[60:61]
	v_lshl_add_u64 v[246:247], v[244:245], 0, s[20:21]
	global_store_short_d16_hi v[244:245], v187, off
	global_store_short_d16_hi v[246:247], v186, off
	v_lshl_add_u64 v[246:247], v[244:245], 0, s[4:5]
	v_lshl_add_u64 v[244:245], v[244:245], 0, s[44:45]
	v_mov_b32_e32 v1, v221
	global_store_short_d16_hi v[246:247], v185, off
	global_store_short_d16_hi v[244:245], v184, off
	s_nop 0
	v_add_u32_e32 v197, 0xfffff000, v1
	v_lshrrev_b32_e32 v2, 8, v1
	v_ashrrev_i32_e32 v197, 10, v197
	v_cndmask_b32_e64 v2, v197, v2, s[40:41]
	v_and_b32_e32 v1, s82, v1
	v_lshl_add_u32 v2, v2, 9, v0
	v_or_b32_e32 v1, s65, v1
	v_lshl_add_u32 v2, v2, s68, v1
	v_lshl_add_u64 v[244:245], v[2:3], 1, s[60:61]
	v_lshl_add_u64 v[246:247], v[244:245], 0, s[20:21]
	global_store_short_d16_hi v[244:245], v179, off
	global_store_short_d16_hi v[246:247], v178, off
	v_lshl_add_u64 v[246:247], v[244:245], 0, s[4:5]
	v_lshl_add_u64 v[244:245], v[244:245], 0, s[44:45]
	v_mov_b32_e32 v1, v220
	global_store_short_d16_hi v[246:247], v177, off
	global_store_short_d16_hi v[244:245], v176, off
	s_nop 0
	v_add_u32_e32 v197, 0xfffff000, v1
	v_lshrrev_b32_e32 v2, 8, v1
	v_ashrrev_i32_e32 v197, 10, v197
	v_cndmask_b32_e64 v2, v197, v2, s[40:41]
	v_and_b32_e32 v1, s82, v1
	v_lshl_add_u32 v2, v2, 9, v0
	v_or_b32_e32 v1, s65, v1
	v_lshl_add_u32 v2, v2, s68, v1
	v_lshl_add_u64 v[244:245], v[2:3], 1, s[60:61]
	v_lshl_add_u64 v[246:247], v[244:245], 0, s[20:21]
	global_store_short_d16_hi v[244:245], v175, off
	global_store_short_d16_hi v[246:247], v174, off
	v_lshl_add_u64 v[246:247], v[244:245], 0, s[4:5]
	v_lshl_add_u64 v[244:245], v[244:245], 0, s[44:45]
	v_mov_b32_e32 v1, v195
	global_store_short_d16_hi v[246:247], v173, off
	global_store_short_d16_hi v[244:245], v172, off
	s_nop 0
	v_add_u32_e32 v197, 0xfffff000, v1
	v_lshrrev_b32_e32 v2, 8, v1
	v_ashrrev_i32_e32 v197, 10, v197
	v_cndmask_b32_e64 v2, v197, v2, s[40:41]
	v_and_b32_e32 v1, s82, v1
	v_lshl_add_u32 v2, v2, 9, v0
	v_or_b32_e32 v1, s65, v1
	v_lshl_add_u32 v2, v2, s68, v1
	v_lshl_add_u64 v[244:245], v[2:3], 1, s[60:61]
	v_lshl_add_u64 v[246:247], v[244:245], 0, s[20:21]
	global_store_short_d16_hi v[244:245], v171, off
	global_store_short_d16_hi v[246:247], v170, off
	v_lshl_add_u64 v[246:247], v[244:245], 0, s[4:5]
	v_lshl_add_u64 v[244:245], v[244:245], 0, s[44:45]
	v_mov_b32_e32 v1, v194
	global_store_short_d16_hi v[246:247], v169, off
	global_store_short_d16_hi v[244:245], v168, off
	s_nop 0
	v_add_u32_e32 v197, 0xfffff000, v1
	v_lshrrev_b32_e32 v2, 8, v1
	v_ashrrev_i32_e32 v197, 10, v197
	v_cndmask_b32_e64 v2, v197, v2, s[40:41]
	v_and_b32_e32 v1, s82, v1
	v_lshl_add_u32 v2, v2, 9, v0
	v_or_b32_e32 v1, s65, v1
	v_lshl_add_u32 v2, v2, s68, v1
	v_lshl_add_u64 v[244:245], v[2:3], 1, s[60:61]
	v_lshl_add_u64 v[246:247], v[244:245], 0, s[20:21]
	global_store_short_d16_hi v[244:245], v167, off
	global_store_short_d16_hi v[246:247], v166, off
	v_lshl_add_u64 v[246:247], v[244:245], 0, s[4:5]
	v_lshl_add_u64 v[244:245], v[244:245], 0, s[44:45]
	v_mov_b32_e32 v1, v225
	global_store_short_d16_hi v[246:247], v165, off
	global_store_short_d16_hi v[244:245], v164, off
	v_add_u32_e32 v0, 16, v0
	v_add_u32_e32 v197, 0xfffff000, v1
	v_lshrrev_b32_e32 v2, 8, v1
	v_ashrrev_i32_e32 v197, 10, v197
	v_cndmask_b32_e64 v2, v197, v2, s[40:41]
	v_and_b32_e32 v1, s82, v1
	v_lshl_add_u32 v2, v2, 9, v0
	v_or_b32_e32 v1, s65, v1
	v_lshl_add_u32 v2, v2, s68, v1
	v_lshl_add_u64 v[244:245], v[2:3], 1, s[60:61]
	v_lshl_add_u64 v[246:247], v[244:245], 0, s[20:21]
	global_store_short_d16_hi v[244:245], v163, off
	global_store_short_d16_hi v[246:247], v162, off
	v_lshl_add_u64 v[246:247], v[244:245], 0, s[4:5]
	v_lshl_add_u64 v[244:245], v[244:245], 0, s[44:45]
	v_mov_b32_e32 v1, v224
	global_store_short_d16_hi v[246:247], v161, off
	global_store_short_d16_hi v[244:245], v160, off
	s_nop 0
	v_add_u32_e32 v197, 0xfffff000, v1
	v_lshrrev_b32_e32 v2, 8, v1
	v_ashrrev_i32_e32 v197, 10, v197
	v_cndmask_b32_e64 v2, v197, v2, s[40:41]
	v_and_b32_e32 v1, s82, v1
	v_lshl_add_u32 v2, v2, 9, v0
	v_or_b32_e32 v1, s65, v1
	v_lshl_add_u32 v2, v2, s68, v1
	v_lshl_add_u64 v[244:245], v[2:3], 1, s[60:61]
	v_lshl_add_u64 v[246:247], v[244:245], 0, s[20:21]
	global_store_short_d16_hi v[244:245], v159, off
	global_store_short_d16_hi v[246:247], v158, off
	v_lshl_add_u64 v[246:247], v[244:245], 0, s[4:5]
	v_lshl_add_u64 v[244:245], v[244:245], 0, s[44:45]
	v_mov_b32_e32 v1, v223
	global_store_short_d16_hi v[246:247], v157, off
	global_store_short_d16_hi v[244:245], v156, off
	s_nop 0
	v_add_u32_e32 v197, 0xfffff000, v1
	v_lshrrev_b32_e32 v2, 8, v1
	v_ashrrev_i32_e32 v197, 10, v197
	v_cndmask_b32_e64 v2, v197, v2, s[40:41]
	v_and_b32_e32 v1, s82, v1
	v_lshl_add_u32 v2, v2, 9, v0
	v_or_b32_e32 v1, s65, v1
	v_lshl_add_u32 v2, v2, s68, v1
	v_lshl_add_u64 v[244:245], v[2:3], 1, s[60:61]
	v_lshl_add_u64 v[246:247], v[244:245], 0, s[20:21]
	global_store_short_d16_hi v[244:245], v155, off
	global_store_short_d16_hi v[246:247], v154, off
	v_lshl_add_u64 v[246:247], v[244:245], 0, s[4:5]
	v_lshl_add_u64 v[244:245], v[244:245], 0, s[44:45]
	v_mov_b32_e32 v1, v222
	global_store_short_d16_hi v[246:247], v153, off
	global_store_short_d16_hi v[244:245], v152, off
	s_nop 0
	v_add_u32_e32 v197, 0xfffff000, v1
	v_lshrrev_b32_e32 v2, 8, v1
	v_ashrrev_i32_e32 v197, 10, v197
	v_cndmask_b32_e64 v2, v197, v2, s[40:41]
	v_and_b32_e32 v1, s82, v1
	v_lshl_add_u32 v2, v2, 9, v0
	v_or_b32_e32 v1, s65, v1
	v_lshl_add_u32 v2, v2, s68, v1
	v_lshl_add_u64 v[244:245], v[2:3], 1, s[60:61]
	v_lshl_add_u64 v[246:247], v[244:245], 0, s[20:21]
	global_store_short_d16_hi v[244:245], v151, off
	global_store_short_d16_hi v[246:247], v150, off
	v_lshl_add_u64 v[246:247], v[244:245], 0, s[4:5]
	v_lshl_add_u64 v[244:245], v[244:245], 0, s[44:45]
	v_mov_b32_e32 v1, v221
	global_store_short_d16_hi v[246:247], v149, off
	global_store_short_d16_hi v[244:245], v148, off
	s_nop 0
	v_add_u32_e32 v197, 0xfffff000, v1
	v_lshrrev_b32_e32 v2, 8, v1
	v_ashrrev_i32_e32 v197, 10, v197
	v_cndmask_b32_e64 v2, v197, v2, s[40:41]
	v_and_b32_e32 v1, s82, v1
	v_lshl_add_u32 v2, v2, 9, v0
	v_or_b32_e32 v1, s65, v1
	v_lshl_add_u32 v2, v2, s68, v1
	v_lshl_add_u64 v[244:245], v[2:3], 1, s[60:61]
	v_lshl_add_u64 v[246:247], v[244:245], 0, s[20:21]
	global_store_short_d16_hi v[244:245], v147, off
	global_store_short_d16_hi v[246:247], v146, off
	v_lshl_add_u64 v[246:247], v[244:245], 0, s[4:5]
	v_lshl_add_u64 v[244:245], v[244:245], 0, s[44:45]
	v_mov_b32_e32 v1, v220
	global_store_short_d16_hi v[246:247], v145, off
	global_store_short_d16_hi v[244:245], v144, off
	s_nop 0
	v_add_u32_e32 v197, 0xfffff000, v1
	v_lshrrev_b32_e32 v2, 8, v1
	v_ashrrev_i32_e32 v197, 10, v197
	v_cndmask_b32_e64 v2, v197, v2, s[40:41]
	v_and_b32_e32 v1, s82, v1
	v_lshl_add_u32 v2, v2, 9, v0
	v_or_b32_e32 v1, s65, v1
	v_lshl_add_u32 v2, v2, s68, v1
	v_lshl_add_u64 v[244:245], v[2:3], 1, s[60:61]
	v_lshl_add_u64 v[246:247], v[244:245], 0, s[20:21]
	global_store_short_d16_hi v[244:245], v143, off
	global_store_short_d16_hi v[246:247], v142, off
	v_lshl_add_u64 v[246:247], v[244:245], 0, s[4:5]
	v_lshl_add_u64 v[244:245], v[244:245], 0, s[44:45]
	v_mov_b32_e32 v1, v195
	global_store_short_d16_hi v[246:247], v141, off
	global_store_short_d16_hi v[244:245], v140, off
	s_nop 0
	v_add_u32_e32 v197, 0xfffff000, v1
	v_lshrrev_b32_e32 v2, 8, v1
	v_ashrrev_i32_e32 v197, 10, v197
	v_cndmask_b32_e64 v2, v197, v2, s[40:41]
	v_and_b32_e32 v1, s82, v1
	v_lshl_add_u32 v2, v2, 9, v0
	v_or_b32_e32 v1, s65, v1
	v_lshl_add_u32 v2, v2, s68, v1
	v_lshl_add_u64 v[244:245], v[2:3], 1, s[60:61]
	v_lshl_add_u64 v[246:247], v[244:245], 0, s[20:21]
	global_store_short_d16_hi v[244:245], v139, off
	global_store_short_d16_hi v[246:247], v138, off
	v_lshl_add_u64 v[246:247], v[244:245], 0, s[4:5]
	v_lshl_add_u64 v[244:245], v[244:245], 0, s[44:45]
	v_mov_b32_e32 v1, v194
	global_store_short_d16_hi v[246:247], v137, off
	global_store_short_d16_hi v[244:245], v136, off
	s_nop 0
	v_add_u32_e32 v197, 0xfffff000, v1
	v_lshrrev_b32_e32 v2, 8, v1
	v_ashrrev_i32_e32 v197, 10, v197
	v_cndmask_b32_e64 v2, v197, v2, s[40:41]
	v_and_b32_e32 v1, s82, v1
	v_lshl_add_u32 v0, v2, 9, v0
	v_or_b32_e32 v1, s65, v1
	v_lshl_add_u32 v2, v0, s68, v1
	v_lshl_add_u64 v[244:245], v[2:3], 1, s[60:61]
	v_lshl_add_u64 v[246:247], v[244:245], 0, s[20:21]
	global_store_short_d16_hi v[244:245], v135, off
	global_store_short_d16_hi v[246:247], v134, off
	v_lshl_add_u64 v[246:247], v[244:245], 0, s[4:5]
	v_lshl_add_u64 v[244:245], v[244:245], 0, s[44:45]
	global_store_short_d16_hi v[246:247], v133, off
	global_store_short_d16_hi v[244:245], v132, off
	s_mov_b64 s[4:5], 0

.LBB0_1390:
	s_or_b32 s80, s67, 0x80
	s_cmpk_lt_i32 s80, 0x280
	s_mov_b64 s[4:5], -1
	s_cbranch_scc1 .LBB0_1485
	s_cmpk_lt_u32 s67, 0x300
	s_cbranch_scc1 .LBB0_1451
	s_cmpk_lt_u32 s67, 0x500
	s_cbranch_scc1 .LBB0_1448
	s_cmpk_lt_u32 s67, 0x700
	s_cbranch_scc1 .LBB0_1430
	s_cmpk_lt_u32 s67, 0x900
	s_cbranch_scc0 .Lts_fast1
	v_bfe_u32 v0, v120, 16, 1
	v_add3_u32 v0, v120, v0, s37
	v_lshrrev_b32_e32 v167, 16, v0
	v_bfe_u32 v0, v121, 16, 1
	v_add3_u32 v0, v121, v0, s37
	v_lshrrev_b32_e32 v166, 16, v0
	v_bfe_u32 v0, v122, 16, 1
	v_add3_u32 v0, v122, v0, s37
	v_lshrrev_b32_e32 v165, 16, v0
	v_bfe_u32 v0, v123, 16, 1
	v_add3_u32 v0, v123, v0, s37
	s_cmpk_lt_u32 s67, 0x900
	v_lshrrev_b32_e32 v164, 16, v0
	s_cbranch_scc1 .LBB0_1396
	v_mov_b32_e32 v1, v225
	v_add_u32_e32 v0, s80, v233
	v_add_u32_e32 v168, 0xfffff000, v1
	v_lshrrev_b32_e32 v2, 8, v1
	v_ashrrev_i32_e32 v168, 10, v168
	v_cndmask_b32_e64 v2, v168, v2, s[40:41]
	v_and_b32_e32 v1, s82, v1
	v_lshl_add_u32 v2, v2, 9, v0
	v_or_b32_e32 v1, s65, v1
	v_lshl_add_u32 v2, v2, s68, v1
	v_lshl_add_u64 v[168:169], v[2:3], 1, s[60:61]
	s_lshl_b32 s20, s64, 1
	v_lshl_add_u64 v[170:171], v[168:169], 0, s[20:21]
	s_lshl_b32 s4, s63, 1
	s_mov_b32 s5, s21
	s_lshl_b32 s44, s62, 1
	s_mov_b32 s45, s21
	global_store_short v[168:169], v167, off
	global_store_short v[170:171], v166, off
	v_lshl_add_u64 v[170:171], v[168:169], 0, s[4:5]
	v_lshl_add_u64 v[168:169], v[168:169], 0, s[44:45]
	v_mov_b32_e32 v1, v224
	global_store_short v[170:171], v165, off
	global_store_short v[168:169], v164, off
	s_nop 0
	v_add_u32_e32 v168, 0xfffff000, v1
	v_lshrrev_b32_e32 v2, 8, v1
	v_ashrrev_i32_e32 v168, 10, v168
	v_cndmask_b32_e64 v2, v168, v2, s[40:41]
	v_and_b32_e32 v1, s82, v1
	v_lshl_add_u32 v2, v2, 9, v0
	v_or_b32_e32 v1, s65, v1
	v_lshl_add_u32 v2, v2, s68, v1
	v_bfe_u32 v1, v104, 16, 1
	v_lshl_add_u64 v[168:169], v[2:3], 1, s[60:61]
	v_add3_u32 v1, v104, v1, s37
	global_store_short_d16_hi v[168:169], v1, off
	v_bfe_u32 v1, v105, 16, 1
	v_lshl_add_u64 v[170:171], v[168:169], 0, s[20:21]
	v_add3_u32 v1, v105, v1, s37
	global_store_short_d16_hi v[170:171], v1, off
	v_bfe_u32 v1, v106, 16, 1
	v_lshl_add_u64 v[170:171], v[168:169], 0, s[4:5]
	v_add3_u32 v1, v106, v1, s37
	global_store_short_d16_hi v[170:171], v1, off
	v_bfe_u32 v1, v107, 16, 1
	v_lshl_add_u64 v[168:169], v[168:169], 0, s[44:45]
	v_add3_u32 v1, v107, v1, s37
	global_store_short_d16_hi v[168:169], v1, off
	v_mov_b32_e32 v1, v223
	s_nop 0
	v_add_u32_e32 v168, 0xfffff000, v1
	v_lshrrev_b32_e32 v2, 8, v1
	v_ashrrev_i32_e32 v168, 10, v168
	v_cndmask_b32_e64 v2, v168, v2, s[40:41]
	v_and_b32_e32 v1, s82, v1
	v_lshl_add_u32 v2, v2, 9, v0
	v_or_b32_e32 v1, s65, v1
	v_lshl_add_u32 v2, v2, s68, v1
	v_bfe_u32 v1, v88, 16, 1
	v_lshl_add_u64 v[168:169], v[2:3], 1, s[60:61]
	v_add3_u32 v1, v88, v1, s37
	global_store_short_d16_hi v[168:169], v1, off
	v_bfe_u32 v1, v89, 16, 1
	v_lshl_add_u64 v[170:171], v[168:169], 0, s[20:21]
	v_add3_u32 v1, v89, v1, s37
	global_store_short_d16_hi v[170:171], v1, off
	v_bfe_u32 v1, v90, 16, 1
	v_lshl_add_u64 v[170:171], v[168:169], 0, s[4:5]
	v_add3_u32 v1, v90, v1, s37
	global_store_short_d16_hi v[170:171], v1, off
	v_bfe_u32 v1, v91, 16, 1
	v_lshl_add_u64 v[168:169], v[168:169], 0, s[44:45]
	v_add3_u32 v1, v91, v1, s37
	global_store_short_d16_hi v[168:169], v1, off
	v_mov_b32_e32 v1, v222
	s_nop 0
	v_add_u32_e32 v168, 0xfffff000, v1
	v_lshrrev_b32_e32 v2, 8, v1
	v_ashrrev_i32_e32 v168, 10, v168
	v_cndmask_b32_e64 v2, v168, v2, s[40:41]
	v_and_b32_e32 v1, s82, v1
	v_lshl_add_u32 v2, v2, 9, v0
	v_or_b32_e32 v1, s65, v1
	v_lshl_add_u32 v2, v2, s68, v1
	v_bfe_u32 v1, v72, 16, 1
	v_lshl_add_u64 v[168:169], v[2:3], 1, s[60:61]
	v_add3_u32 v1, v72, v1, s37
	global_store_short_d16_hi v[168:169], v1, off
	v_bfe_u32 v1, v73, 16, 1
	v_lshl_add_u64 v[170:171], v[168:169], 0, s[20:21]
	v_add3_u32 v1, v73, v1, s37
	global_store_short_d16_hi v[170:171], v1, off
	v_bfe_u32 v1, v74, 16, 1
	v_lshl_add_u64 v[170:171], v[168:169], 0, s[4:5]
	v_add3_u32 v1, v74, v1, s37
	global_store_short_d16_hi v[170:171], v1, off
	v_bfe_u32 v1, v75, 16, 1
	v_lshl_add_u64 v[168:169], v[168:169], 0, s[44:45]
	v_add3_u32 v1, v75, v1, s37
	global_store_short_d16_hi v[168:169], v1, off
	v_mov_b32_e32 v1, v221
	s_nop 0
	v_add_u32_e32 v168, 0xfffff000, v1
	v_lshrrev_b32_e32 v2, 8, v1
	v_ashrrev_i32_e32 v168, 10, v168
	v_cndmask_b32_e64 v2, v168, v2, s[40:41]
	v_and_b32_e32 v1, s82, v1
	v_lshl_add_u32 v2, v2, 9, v0
	v_or_b32_e32 v1, s65, v1
	v_lshl_add_u32 v2, v2, s68, v1
	v_bfe_u32 v1, v56, 16, 1
	v_lshl_add_u64 v[168:169], v[2:3], 1, s[60:61]
	v_add3_u32 v1, v56, v1, s37
	global_store_short_d16_hi v[168:169], v1, off
	v_bfe_u32 v1, v57, 16, 1
	v_lshl_add_u64 v[170:171], v[168:169], 0, s[20:21]
	v_add3_u32 v1, v57, v1, s37
	global_store_short_d16_hi v[170:171], v1, off
	v_bfe_u32 v1, v58, 16, 1
	v_lshl_add_u64 v[170:171], v[168:169], 0, s[4:5]
	v_add3_u32 v1, v58, v1, s37
	global_store_short_d16_hi v[170:171], v1, off
	v_bfe_u32 v1, v59, 16, 1
	v_lshl_add_u64 v[168:169], v[168:169], 0, s[44:45]
	v_add3_u32 v1, v59, v1, s37
	global_store_short_d16_hi v[168:169], v1, off
	v_mov_b32_e32 v1, v220
	s_nop 0
	v_add_u32_e32 v168, 0xfffff000, v1
	v_lshrrev_b32_e32 v2, 8, v1
	v_ashrrev_i32_e32 v168, 10, v168
	v_cndmask_b32_e64 v2, v168, v2, s[40:41]
	v_and_b32_e32 v1, s82, v1
	v_lshl_add_u32 v2, v2, 9, v0
	v_or_b32_e32 v1, s65, v1
	v_lshl_add_u32 v2, v2, s68, v1
	v_bfe_u32 v1, v40, 16, 1
	v_lshl_add_u64 v[168:169], v[2:3], 1, s[60:61]
	v_add3_u32 v1, v40, v1, s37
	global_store_short_d16_hi v[168:169], v1, off
	v_bfe_u32 v1, v41, 16, 1
	v_lshl_add_u64 v[170:171], v[168:169], 0, s[20:21]
	v_add3_u32 v1, v41, v1, s37
	global_store_short_d16_hi v[170:171], v1, off
	v_bfe_u32 v1, v42, 16, 1
	v_lshl_add_u64 v[170:171], v[168:169], 0, s[4:5]
	v_add3_u32 v1, v42, v1, s37
	global_store_short_d16_hi v[170:171], v1, off
	v_bfe_u32 v1, v43, 16, 1
	v_lshl_add_u64 v[168:169], v[168:169], 0, s[44:45]
	v_add3_u32 v1, v43, v1, s37
	global_store_short_d16_hi v[168:169], v1, off
	v_mov_b32_e32 v1, v195
	s_nop 0
	v_add_u32_e32 v168, 0xfffff000, v1
	v_lshrrev_b32_e32 v2, 8, v1
	v_ashrrev_i32_e32 v168, 10, v168
	v_cndmask_b32_e64 v2, v168, v2, s[40:41]
	v_and_b32_e32 v1, s82, v1
	v_lshl_add_u32 v2, v2, 9, v0
	v_or_b32_e32 v1, s65, v1
	v_lshl_add_u32 v2, v2, s68, v1
	v_bfe_u32 v1, v24, 16, 1
	v_lshl_add_u64 v[168:169], v[2:3], 1, s[60:61]
	v_add3_u32 v1, v24, v1, s37
	global_store_short_d16_hi v[168:169], v1, off
	v_bfe_u32 v1, v25, 16, 1
	v_lshl_add_u64 v[170:171], v[168:169], 0, s[20:21]
	v_add3_u32 v1, v25, v1, s37
	global_store_short_d16_hi v[170:171], v1, off
	v_bfe_u32 v1, v26, 16, 1
	v_lshl_add_u64 v[170:171], v[168:169], 0, s[4:5]
	v_add3_u32 v1, v26, v1, s37
	global_store_short_d16_hi v[170:171], v1, off
	v_bfe_u32 v1, v27, 16, 1
	v_lshl_add_u64 v[168:169], v[168:169], 0, s[44:45]
	v_add3_u32 v1, v27, v1, s37
	global_store_short_d16_hi v[168:169], v1, off
	v_mov_b32_e32 v1, v194
	s_nop 0
	v_add_u32_e32 v168, 0xfffff000, v1
	v_lshrrev_b32_e32 v2, 8, v1
	v_ashrrev_i32_e32 v168, 10, v168
	v_cndmask_b32_e64 v2, v168, v2, s[40:41]
	v_and_b32_e32 v1, s82, v1
	v_lshl_add_u32 v2, v2, 9, v0
	v_or_b32_e32 v1, s65, v1
	v_lshl_add_u32 v2, v2, s68, v1
	v_bfe_u32 v1, v8, 16, 1
	v_lshl_add_u64 v[168:169], v[2:3], 1, s[60:61]
	v_add3_u32 v1, v8, v1, s37
	global_store_short_d16_hi v[168:169], v1, off
	v_bfe_u32 v1, v9, 16, 1
	v_lshl_add_u64 v[170:171], v[168:169], 0, s[20:21]
	v_add3_u32 v1, v9, v1, s37
	global_store_short_d16_hi v[170:171], v1, off
	v_bfe_u32 v1, v10, 16, 1
	v_lshl_add_u64 v[170:171], v[168:169], 0, s[4:5]
	v_add3_u32 v1, v10, v1, s37
	global_store_short_d16_hi v[170:171], v1, off
	v_bfe_u32 v1, v11, 16, 1
	v_lshl_add_u64 v[168:169], v[168:169], 0, s[44:45]
	v_add3_u32 v1, v11, v1, s37
	global_store_short_d16_hi v[168:169], v1, off
	v_mov_b32_e32 v1, v225
	v_add_u32_e32 v0, 16, v0
	v_add_u32_e32 v168, 0xfffff000, v1
	v_lshrrev_b32_e32 v2, 8, v1
	v_ashrrev_i32_e32 v168, 10, v168
	v_cndmask_b32_e64 v2, v168, v2, s[40:41]
	v_and_b32_e32 v1, s82, v1
	v_lshl_add_u32 v2, v2, 9, v0
	v_or_b32_e32 v1, s65, v1
	v_lshl_add_u32 v2, v2, s68, v1
	v_bfe_u32 v1, v116, 16, 1
	v_lshl_add_u64 v[168:169], v[2:3], 1, s[60:61]
	v_add3_u32 v1, v116, v1, s37
	global_store_short_d16_hi v[168:169], v1, off
	v_bfe_u32 v1, v117, 16, 1
	v_lshl_add_u64 v[170:171], v[168:169], 0, s[20:21]
	v_add3_u32 v1, v117, v1, s37
	global_store_short_d16_hi v[170:171], v1, off
	v_bfe_u32 v1, v118, 16, 1
	v_lshl_add_u64 v[170:171], v[168:169], 0, s[4:5]
	v_add3_u32 v1, v118, v1, s37
	global_store_short_d16_hi v[170:171], v1, off
	v_bfe_u32 v1, v119, 16, 1
	v_lshl_add_u64 v[168:169], v[168:169], 0, s[44:45]
	v_add3_u32 v1, v119, v1, s37
	global_store_short_d16_hi v[168:169], v1, off
	v_mov_b32_e32 v1, v224
	s_nop 0
	v_add_u32_e32 v168, 0xfffff000, v1
	v_lshrrev_b32_e32 v2, 8, v1
	v_ashrrev_i32_e32 v168, 10, v168
	v_cndmask_b32_e64 v2, v168, v2, s[40:41]
	v_and_b32_e32 v1, s82, v1
	v_lshl_add_u32 v2, v2, 9, v0
	v_or_b32_e32 v1, s65, v1
	v_lshl_add_u32 v2, v2, s68, v1
	v_bfe_u32 v1, v100, 16, 1
	v_lshl_add_u64 v[168:169], v[2:3], 1, s[60:61]
	v_add3_u32 v1, v100, v1, s37
	global_store_short_d16_hi v[168:169], v1, off
	v_bfe_u32 v1, v101, 16, 1
	v_lshl_add_u64 v[170:171], v[168:169], 0, s[20:21]
	v_add3_u32 v1, v101, v1, s37
	global_store_short_d16_hi v[170:171], v1, off
	v_bfe_u32 v1, v102, 16, 1
	v_lshl_add_u64 v[170:171], v[168:169], 0, s[4:5]
	v_add3_u32 v1, v102, v1, s37
	global_store_short_d16_hi v[170:171], v1, off
	v_bfe_u32 v1, v103, 16, 1
	v_lshl_add_u64 v[168:169], v[168:169], 0, s[44:45]
	v_add3_u32 v1, v103, v1, s37
	global_store_short_d16_hi v[168:169], v1, off
	v_mov_b32_e32 v1, v223
	s_nop 0
	v_add_u32_e32 v168, 0xfffff000, v1
	v_lshrrev_b32_e32 v2, 8, v1
	v_ashrrev_i32_e32 v168, 10, v168
	v_cndmask_b32_e64 v2, v168, v2, s[40:41]
	v_and_b32_e32 v1, s82, v1
	v_lshl_add_u32 v2, v2, 9, v0
	v_or_b32_e32 v1, s65, v1
	v_lshl_add_u32 v2, v2, s68, v1
	v_bfe_u32 v1, v84, 16, 1
	v_lshl_add_u64 v[168:169], v[2:3], 1, s[60:61]
	v_add3_u32 v1, v84, v1, s37
	global_store_short_d16_hi v[168:169], v1, off
	v_bfe_u32 v1, v85, 16, 1
	v_lshl_add_u64 v[170:171], v[168:169], 0, s[20:21]
	v_add3_u32 v1, v85, v1, s37
	global_store_short_d16_hi v[170:171], v1, off
	v_bfe_u32 v1, v86, 16, 1
	v_lshl_add_u64 v[170:171], v[168:169], 0, s[4:5]
	v_add3_u32 v1, v86, v1, s37
	global_store_short_d16_hi v[170:171], v1, off
	v_bfe_u32 v1, v87, 16, 1
	v_lshl_add_u64 v[168:169], v[168:169], 0, s[44:45]
	v_add3_u32 v1, v87, v1, s37
	global_store_short_d16_hi v[168:169], v1, off
	v_mov_b32_e32 v1, v222
	s_nop 0
	v_add_u32_e32 v168, 0xfffff000, v1
	v_lshrrev_b32_e32 v2, 8, v1
	v_ashrrev_i32_e32 v168, 10, v168
	v_cndmask_b32_e64 v2, v168, v2, s[40:41]
	v_and_b32_e32 v1, s82, v1
	v_lshl_add_u32 v2, v2, 9, v0
	v_or_b32_e32 v1, s65, v1
	v_lshl_add_u32 v2, v2, s68, v1
	v_bfe_u32 v1, v68, 16, 1
	v_lshl_add_u64 v[168:169], v[2:3], 1, s[60:61]
	v_add3_u32 v1, v68, v1, s37
	global_store_short_d16_hi v[168:169], v1, off
	v_bfe_u32 v1, v69, 16, 1
	v_lshl_add_u64 v[170:171], v[168:169], 0, s[20:21]
	v_add3_u32 v1, v69, v1, s37
	global_store_short_d16_hi v[170:171], v1, off
	v_bfe_u32 v1, v70, 16, 1
	v_lshl_add_u64 v[170:171], v[168:169], 0, s[4:5]
	v_add3_u32 v1, v70, v1, s37
	global_store_short_d16_hi v[170:171], v1, off
	v_bfe_u32 v1, v71, 16, 1
	v_lshl_add_u64 v[168:169], v[168:169], 0, s[44:45]
	v_add3_u32 v1, v71, v1, s37
	global_store_short_d16_hi v[168:169], v1, off
	v_mov_b32_e32 v1, v221
	s_nop 0
	v_add_u32_e32 v168, 0xfffff000, v1
	v_lshrrev_b32_e32 v2, 8, v1
	v_ashrrev_i32_e32 v168, 10, v168
	v_cndmask_b32_e64 v2, v168, v2, s[40:41]
	v_and_b32_e32 v1, s82, v1
	v_lshl_add_u32 v2, v2, 9, v0
	v_or_b32_e32 v1, s65, v1
	v_lshl_add_u32 v2, v2, s68, v1
	v_bfe_u32 v1, v52, 16, 1
	v_lshl_add_u64 v[168:169], v[2:3], 1, s[60:61]
	v_add3_u32 v1, v52, v1, s37
	global_store_short_d16_hi v[168:169], v1, off
	v_bfe_u32 v1, v53, 16, 1
	v_lshl_add_u64 v[170:171], v[168:169], 0, s[20:21]
	v_add3_u32 v1, v53, v1, s37
	global_store_short_d16_hi v[170:171], v1, off
	v_bfe_u32 v1, v54, 16, 1
	v_lshl_add_u64 v[170:171], v[168:169], 0, s[4:5]
	v_add3_u32 v1, v54, v1, s37
	global_store_short_d16_hi v[170:171], v1, off
	v_bfe_u32 v1, v55, 16, 1
	v_lshl_add_u64 v[168:169], v[168:169], 0, s[44:45]
	v_add3_u32 v1, v55, v1, s37
	global_store_short_d16_hi v[168:169], v1, off
	v_mov_b32_e32 v1, v220
	s_nop 0
	v_add_u32_e32 v168, 0xfffff000, v1
	v_lshrrev_b32_e32 v2, 8, v1
	v_ashrrev_i32_e32 v168, 10, v168
	v_cndmask_b32_e64 v2, v168, v2, s[40:41]
	v_and_b32_e32 v1, s82, v1
	v_lshl_add_u32 v2, v2, 9, v0
	v_or_b32_e32 v1, s65, v1
	v_lshl_add_u32 v2, v2, s68, v1
	v_bfe_u32 v1, v36, 16, 1
	v_lshl_add_u64 v[168:169], v[2:3], 1, s[60:61]
	v_add3_u32 v1, v36, v1, s37
	global_store_short_d16_hi v[168:169], v1, off
	v_bfe_u32 v1, v37, 16, 1
	v_lshl_add_u64 v[170:171], v[168:169], 0, s[20:21]
	v_add3_u32 v1, v37, v1, s37
	global_store_short_d16_hi v[170:171], v1, off
	v_bfe_u32 v1, v38, 16, 1
	v_lshl_add_u64 v[170:171], v[168:169], 0, s[4:5]
	v_add3_u32 v1, v38, v1, s37
	global_store_short_d16_hi v[170:171], v1, off
	v_bfe_u32 v1, v39, 16, 1
	v_lshl_add_u64 v[168:169], v[168:169], 0, s[44:45]
	v_add3_u32 v1, v39, v1, s37
	global_store_short_d16_hi v[168:169], v1, off
	v_mov_b32_e32 v1, v195
	s_nop 0
	v_add_u32_e32 v168, 0xfffff000, v1
	v_lshrrev_b32_e32 v2, 8, v1
	v_ashrrev_i32_e32 v168, 10, v168
	v_cndmask_b32_e64 v2, v168, v2, s[40:41]
	v_and_b32_e32 v1, s82, v1
	v_lshl_add_u32 v2, v2, 9, v0
	v_or_b32_e32 v1, s65, v1
	v_lshl_add_u32 v2, v2, s68, v1
	v_bfe_u32 v1, v20, 16, 1
	v_lshl_add_u64 v[168:169], v[2:3], 1, s[60:61]
	v_add3_u32 v1, v20, v1, s37
	global_store_short_d16_hi v[168:169], v1, off
	v_bfe_u32 v1, v21, 16, 1
	v_lshl_add_u64 v[170:171], v[168:169], 0, s[20:21]
	v_add3_u32 v1, v21, v1, s37
	global_store_short_d16_hi v[170:171], v1, off
	v_bfe_u32 v1, v22, 16, 1
	v_lshl_add_u64 v[170:171], v[168:169], 0, s[4:5]
	v_add3_u32 v1, v22, v1, s37
	global_store_short_d16_hi v[170:171], v1, off
	v_bfe_u32 v1, v23, 16, 1
	v_lshl_add_u64 v[168:169], v[168:169], 0, s[44:45]
	v_add3_u32 v1, v23, v1, s37
	global_store_short_d16_hi v[168:169], v1, off
	v_mov_b32_e32 v1, v194
	s_nop 0
	v_add_u32_e32 v168, 0xfffff000, v1
	v_lshrrev_b32_e32 v2, 8, v1
	v_ashrrev_i32_e32 v168, 10, v168
	v_cndmask_b32_e64 v2, v168, v2, s[40:41]
	v_and_b32_e32 v1, s82, v1
	v_lshl_add_u32 v0, v2, 9, v0
	v_or_b32_e32 v1, s65, v1
	v_lshl_add_u32 v2, v0, s68, v1
	v_bfe_u32 v0, v4, 16, 1
	v_lshl_add_u64 v[168:169], v[2:3], 1, s[60:61]
	v_add3_u32 v0, v4, v0, s37
	global_store_short_d16_hi v[168:169], v0, off
	v_bfe_u32 v0, v5, 16, 1
	v_lshl_add_u64 v[170:171], v[168:169], 0, s[20:21]
	v_add3_u32 v0, v5, v0, s37
	global_store_short_d16_hi v[170:171], v0, off
	v_bfe_u32 v0, v6, 16, 1
	v_lshl_add_u64 v[170:171], v[168:169], 0, s[4:5]
	v_add3_u32 v0, v6, v0, s37
	global_store_short_d16_hi v[170:171], v0, off
	v_bfe_u32 v0, v7, 16, 1
	v_lshl_add_u64 v[168:169], v[168:169], 0, s[44:45]
	v_add3_u32 v0, v7, v0, s37
	s_mov_b64 s[4:5], 0
	global_store_short_d16_hi v[168:169], v0, off

.Lts_fast0:
	v_mov_b32_e32 v196, v202
	v_and_b32_e32 v132, 3, v202
	s_lshl_b32 s20, s64, 1
	s_add_i32 vcc_lo, s20, -2
	v_and_b32_e32 v133, 1, v132
	v_mul_lo_u32 v134, v132, vcc_lo
	v_mov_b32_e32 v135, 0
	v_cmp_eq_u32_e64 s[4:5], 1, v133
	v_and_b32_e32 v133, 2, v132
	v_mov_b32_e32 v136, 0x5040100
	v_mov_b32_e32 v137, 0x3020706
	v_cmp_eq_u32_e64 s[44:45], 2, v133
	s_nop 1
	v_cndmask_b32_e64 v136, v136, v137, s[4:5]
	v_add_u32_e32 v138, s67, v233
	v_cvt_pk_bf16_f32 v140, v128, v129
	v_cvt_pk_bf16_f32 v141, v130, v131
	v_add_u32_e32 v152, 0xfffff000, v225
	v_lshrrev_b32_e32 v153, 8, v225
	v_ashrrev_i32_e32 v152, 10, v152
	v_cndmask_b32_e64 v153, v152, v153, s[40:41]
	v_and_b32_e32 v152, s82, v225
	v_lshl_add_u32 v153, v153, 9, v138
	v_or_b32_e32 v152, s65, v152
	v_lshl_add_u32 v2, v153, s68, v152
	v_mov_b32_dpp v142, v140 quad_perm:[1,0,3,2] row_mask:0xf bank_mask:0xf
	v_mov_b32_dpp v143, v141 quad_perm:[1,0,3,2] row_mask:0xf bank_mask:0xf
	v_lshl_add_u64 v[150:151], v[2:3], 1, s[60:61]
	v_lshl_add_u64 v[150:151], v[150:151], 0, v[134:135]
	v_perm_b32 v144, v142, v140, v136
	v_perm_b32 v145, v143, v141, v136
	s_nop 1
	v_mov_b32_dpp v146, v144 quad_perm:[2,3,0,1] row_mask:0xf bank_mask:0xf
	v_mov_b32_dpp v147, v145 quad_perm:[2,3,0,1] row_mask:0xf bank_mask:0xf
	s_nop 0
	v_cndmask_b32_e64 v148, v144, v147, s[44:45]
	v_cndmask_b32_e64 v149, v146, v145, s[44:45]
	global_store_dwordx2 v[150:151], v[148:149], off
	v_cvt_pk_bf16_f32 v156, v112, v113
	v_cvt_pk_bf16_f32 v157, v114, v115
	v_add_u32_e32 v168, 0xfffff000, v224
	v_lshrrev_b32_e32 v169, 8, v224
	v_ashrrev_i32_e32 v168, 10, v168
	v_cndmask_b32_e64 v169, v168, v169, s[40:41]
	v_and_b32_e32 v168, s82, v224
	v_lshl_add_u32 v169, v169, 9, v138
	v_or_b32_e32 v168, s65, v168
	v_lshl_add_u32 v2, v169, s68, v168
	v_mov_b32_dpp v158, v156 quad_perm:[1,0,3,2] row_mask:0xf bank_mask:0xf
	v_mov_b32_dpp v159, v157 quad_perm:[1,0,3,2] row_mask:0xf bank_mask:0xf
	v_lshl_add_u64 v[166:167], v[2:3], 1, s[60:61]
	v_lshl_add_u64 v[166:167], v[166:167], 0, v[134:135]
	v_perm_b32 v160, v158, v156, v136
	v_perm_b32 v161, v159, v157, v136
	s_nop 1
	v_mov_b32_dpp v162, v160 quad_perm:[2,3,0,1] row_mask:0xf bank_mask:0xf
	v_mov_b32_dpp v163, v161 quad_perm:[2,3,0,1] row_mask:0xf bank_mask:0xf
	s_nop 0
	v_cndmask_b32_e64 v164, v160, v163, s[44:45]
	v_cndmask_b32_e64 v165, v162, v161, s[44:45]
	global_store_dwordx2 v[166:167], v[164:165], off
	v_cvt_pk_bf16_f32 v140, v96, v97
	v_cvt_pk_bf16_f32 v141, v98, v99
	v_add_u32_e32 v152, 0xfffff000, v223
	v_lshrrev_b32_e32 v153, 8, v223
	v_ashrrev_i32_e32 v152, 10, v152
	v_cndmask_b32_e64 v153, v152, v153, s[40:41]
	v_and_b32_e32 v152, s82, v223
	v_lshl_add_u32 v153, v153, 9, v138
	v_or_b32_e32 v152, s65, v152
	v_lshl_add_u32 v2, v153, s68, v152
	v_mov_b32_dpp v142, v140 quad_perm:[1,0,3,2] row_mask:0xf bank_mask:0xf
	v_mov_b32_dpp v143, v141 quad_perm:[1,0,3,2] row_mask:0xf bank_mask:0xf
	v_lshl_add_u64 v[150:151], v[2:3], 1, s[60:61]
	v_lshl_add_u64 v[150:151], v[150:151], 0, v[134:135]
	v_perm_b32 v144, v142, v140, v136
	v_perm_b32 v145, v143, v141, v136
	s_nop 1
	v_mov_b32_dpp v146, v144 quad_perm:[2,3,0,1] row_mask:0xf bank_mask:0xf
	v_mov_b32_dpp v147, v145 quad_perm:[2,3,0,1] row_mask:0xf bank_mask:0xf
	s_nop 0
	v_cndmask_b32_e64 v148, v144, v147, s[44:45]
	v_cndmask_b32_e64 v149, v146, v145, s[44:45]
	global_store_dwordx2 v[150:151], v[148:149], off
	v_cvt_pk_bf16_f32 v156, v80, v81
	v_cvt_pk_bf16_f32 v157, v82, v83
	v_add_u32_e32 v168, 0xfffff000, v222
	v_lshrrev_b32_e32 v169, 8, v222
	v_ashrrev_i32_e32 v168, 10, v168
	v_cndmask_b32_e64 v169, v168, v169, s[40:41]
	v_and_b32_e32 v168, s82, v222
	v_lshl_add_u32 v169, v169, 9, v138
	v_or_b32_e32 v168, s65, v168
	v_lshl_add_u32 v2, v169, s68, v168
	v_mov_b32_dpp v158, v156 quad_perm:[1,0,3,2] row_mask:0xf bank_mask:0xf
	v_mov_b32_dpp v159, v157 quad_perm:[1,0,3,2] row_mask:0xf bank_mask:0xf
	v_lshl_add_u64 v[166:167], v[2:3], 1, s[60:61]
	v_lshl_add_u64 v[166:167], v[166:167], 0, v[134:135]
	v_perm_b32 v160, v158, v156, v136
	v_perm_b32 v161, v159, v157, v136
	s_nop 1
	v_mov_b32_dpp v162, v160 quad_perm:[2,3,0,1] row_mask:0xf bank_mask:0xf
	v_mov_b32_dpp v163, v161 quad_perm:[2,3,0,1] row_mask:0xf bank_mask:0xf
	s_nop 0
	v_cndmask_b32_e64 v164, v160, v163, s[44:45]
	v_cndmask_b32_e64 v165, v162, v161, s[44:45]
	global_store_dwordx2 v[166:167], v[164:165], off
	v_cvt_pk_bf16_f32 v140, v64, v65
	v_cvt_pk_bf16_f32 v141, v66, v67
	v_add_u32_e32 v152, 0xfffff000, v221
	v_lshrrev_b32_e32 v153, 8, v221
	v_ashrrev_i32_e32 v152, 10, v152
	v_cndmask_b32_e64 v153, v152, v153, s[40:41]
	v_and_b32_e32 v152, s82, v221
	v_lshl_add_u32 v153, v153, 9, v138
	v_or_b32_e32 v152, s65, v152
	v_lshl_add_u32 v2, v153, s68, v152
	v_mov_b32_dpp v142, v140 quad_perm:[1,0,3,2] row_mask:0xf bank_mask:0xf
	v_mov_b32_dpp v143, v141 quad_perm:[1,0,3,2] row_mask:0xf bank_mask:0xf
	v_lshl_add_u64 v[150:151], v[2:3], 1, s[60:61]
	v_lshl_add_u64 v[150:151], v[150:151], 0, v[134:135]
	v_perm_b32 v144, v142, v140, v136
	v_perm_b32 v145, v143, v141, v136
	s_nop 1
	v_mov_b32_dpp v146, v144 quad_perm:[2,3,0,1] row_mask:0xf bank_mask:0xf
	v_mov_b32_dpp v147, v145 quad_perm:[2,3,0,1] row_mask:0xf bank_mask:0xf
	s_nop 0
	v_cndmask_b32_e64 v148, v144, v147, s[44:45]
	v_cndmask_b32_e64 v149, v146, v145, s[44:45]
	global_store_dwordx2 v[150:151], v[148:149], off
	v_cvt_pk_bf16_f32 v156, v48, v49
	v_cvt_pk_bf16_f32 v157, v50, v51
	v_add_u32_e32 v168, 0xfffff000, v220
	v_lshrrev_b32_e32 v169, 8, v220
	v_ashrrev_i32_e32 v168, 10, v168
	v_cndmask_b32_e64 v169, v168, v169, s[40:41]
	v_and_b32_e32 v168, s82, v220
	v_lshl_add_u32 v169, v169, 9, v138
	v_or_b32_e32 v168, s65, v168
	v_lshl_add_u32 v2, v169, s68, v168
	v_mov_b32_dpp v158, v156 quad_perm:[1,0,3,2] row_mask:0xf bank_mask:0xf
	v_mov_b32_dpp v159, v157 quad_perm:[1,0,3,2] row_mask:0xf bank_mask:0xf
	v_lshl_add_u64 v[166:167], v[2:3], 1, s[60:61]
	v_lshl_add_u64 v[166:167], v[166:167], 0, v[134:135]
	v_perm_b32 v160, v158, v156, v136
	v_perm_b32 v161, v159, v157, v136
	s_nop 1
	v_mov_b32_dpp v162, v160 quad_perm:[2,3,0,1] row_mask:0xf bank_mask:0xf
	v_mov_b32_dpp v163, v161 quad_perm:[2,3,0,1] row_mask:0xf bank_mask:0xf
	s_nop 0
	v_cndmask_b32_e64 v164, v160, v163, s[44:45]
	v_cndmask_b32_e64 v165, v162, v161, s[44:45]
	global_store_dwordx2 v[166:167], v[164:165], off
	v_cvt_pk_bf16_f32 v140, v32, v33
	v_cvt_pk_bf16_f32 v141, v34, v35
	v_add_u32_e32 v152, 0xfffff000, v195
	v_lshrrev_b32_e32 v153, 8, v195
	v_ashrrev_i32_e32 v152, 10, v152
	v_cndmask_b32_e64 v153, v152, v153, s[40:41]
	v_and_b32_e32 v152, s82, v195
	v_lshl_add_u32 v153, v153, 9, v138
	v_or_b32_e32 v152, s65, v152
	v_lshl_add_u32 v2, v153, s68, v152
	v_mov_b32_dpp v142, v140 quad_perm:[1,0,3,2] row_mask:0xf bank_mask:0xf
	v_mov_b32_dpp v143, v141 quad_perm:[1,0,3,2] row_mask:0xf bank_mask:0xf
	v_lshl_add_u64 v[150:151], v[2:3], 1, s[60:61]
	v_lshl_add_u64 v[150:151], v[150:151], 0, v[134:135]
	v_perm_b32 v144, v142, v140, v136
	v_perm_b32 v145, v143, v141, v136
	s_nop 1
	v_mov_b32_dpp v146, v144 quad_perm:[2,3,0,1] row_mask:0xf bank_mask:0xf
	v_mov_b32_dpp v147, v145 quad_perm:[2,3,0,1] row_mask:0xf bank_mask:0xf
	s_nop 0
	v_cndmask_b32_e64 v148, v144, v147, s[44:45]
	v_cndmask_b32_e64 v149, v146, v145, s[44:45]
	global_store_dwordx2 v[150:151], v[148:149], off
	v_cvt_pk_bf16_f32 v156, v16, v17
	v_cvt_pk_bf16_f32 v157, v18, v19
	v_add_u32_e32 v168, 0xfffff000, v194
	v_lshrrev_b32_e32 v169, 8, v194
	v_ashrrev_i32_e32 v168, 10, v168
	v_cndmask_b32_e64 v169, v168, v169, s[40:41]
	v_and_b32_e32 v168, s82, v194
	v_lshl_add_u32 v169, v169, 9, v138
	v_or_b32_e32 v168, s65, v168
	v_lshl_add_u32 v2, v169, s68, v168
	v_mov_b32_dpp v158, v156 quad_perm:[1,0,3,2] row_mask:0xf bank_mask:0xf
	v_mov_b32_dpp v159, v157 quad_perm:[1,0,3,2] row_mask:0xf bank_mask:0xf
	v_lshl_add_u64 v[166:167], v[2:3], 1, s[60:61]
	v_lshl_add_u64 v[166:167], v[166:167], 0, v[134:135]
	v_perm_b32 v160, v158, v156, v136
	v_perm_b32 v161, v159, v157, v136
	s_nop 1
	v_mov_b32_dpp v162, v160 quad_perm:[2,3,0,1] row_mask:0xf bank_mask:0xf
	v_mov_b32_dpp v163, v161 quad_perm:[2,3,0,1] row_mask:0xf bank_mask:0xf
	s_nop 0
	v_cndmask_b32_e64 v164, v160, v163, s[44:45]
	v_cndmask_b32_e64 v165, v162, v161, s[44:45]
	global_store_dwordx2 v[166:167], v[164:165], off
	v_add_u32_e32 v138, s67, v233
	v_add_u32_e32 v138, 16, v138
	v_cvt_pk_bf16_f32 v140, v124, v125
	v_cvt_pk_bf16_f32 v141, v126, v127
	v_add_u32_e32 v152, 0xfffff000, v225
	v_lshrrev_b32_e32 v153, 8, v225
	v_ashrrev_i32_e32 v152, 10, v152
	v_cndmask_b32_e64 v153, v152, v153, s[40:41]
	v_and_b32_e32 v152, s82, v225
	v_lshl_add_u32 v153, v153, 9, v138
	v_or_b32_e32 v152, s65, v152
	v_lshl_add_u32 v2, v153, s68, v152
	v_mov_b32_dpp v142, v140 quad_perm:[1,0,3,2] row_mask:0xf bank_mask:0xf
	v_mov_b32_dpp v143, v141 quad_perm:[1,0,3,2] row_mask:0xf bank_mask:0xf
	v_lshl_add_u64 v[150:151], v[2:3], 1, s[60:61]
	v_lshl_add_u64 v[150:151], v[150:151], 0, v[134:135]
	v_perm_b32 v144, v142, v140, v136
	v_perm_b32 v145, v143, v141, v136
	s_nop 1
	v_mov_b32_dpp v146, v144 quad_perm:[2,3,0,1] row_mask:0xf bank_mask:0xf
	v_mov_b32_dpp v147, v145 quad_perm:[2,3,0,1] row_mask:0xf bank_mask:0xf
	s_nop 0
	v_cndmask_b32_e64 v148, v144, v147, s[44:45]
	v_cndmask_b32_e64 v149, v146, v145, s[44:45]
	global_store_dwordx2 v[150:151], v[148:149], off
	v_cvt_pk_bf16_f32 v156, v108, v109
	v_cvt_pk_bf16_f32 v157, v110, v111
	v_add_u32_e32 v168, 0xfffff000, v224
	v_lshrrev_b32_e32 v169, 8, v224
	v_ashrrev_i32_e32 v168, 10, v168
	v_cndmask_b32_e64 v169, v168, v169, s[40:41]
	v_and_b32_e32 v168, s82, v224
	v_lshl_add_u32 v169, v169, 9, v138
	v_or_b32_e32 v168, s65, v168
	v_lshl_add_u32 v2, v169, s68, v168
	v_mov_b32_dpp v158, v156 quad_perm:[1,0,3,2] row_mask:0xf bank_mask:0xf
	v_mov_b32_dpp v159, v157 quad_perm:[1,0,3,2] row_mask:0xf bank_mask:0xf
	v_lshl_add_u64 v[166:167], v[2:3], 1, s[60:61]
	v_lshl_add_u64 v[166:167], v[166:167], 0, v[134:135]
	v_perm_b32 v160, v158, v156, v136
	v_perm_b32 v161, v159, v157, v136
	s_nop 1
	v_mov_b32_dpp v162, v160 quad_perm:[2,3,0,1] row_mask:0xf bank_mask:0xf
	v_mov_b32_dpp v163, v161 quad_perm:[2,3,0,1] row_mask:0xf bank_mask:0xf
	s_nop 0
	v_cndmask_b32_e64 v164, v160, v163, s[44:45]
	v_cndmask_b32_e64 v165, v162, v161, s[44:45]
	global_store_dwordx2 v[166:167], v[164:165], off
	v_cvt_pk_bf16_f32 v140, v92, v93
	v_cvt_pk_bf16_f32 v141, v94, v95
	v_add_u32_e32 v152, 0xfffff000, v223
	v_lshrrev_b32_e32 v153, 8, v223
	v_ashrrev_i32_e32 v152, 10, v152
	v_cndmask_b32_e64 v153, v152, v153, s[40:41]
	v_and_b32_e32 v152, s82, v223
	v_lshl_add_u32 v153, v153, 9, v138
	v_or_b32_e32 v152, s65, v152
	v_lshl_add_u32 v2, v153, s68, v152
	v_mov_b32_dpp v142, v140 quad_perm:[1,0,3,2] row_mask:0xf bank_mask:0xf
	v_mov_b32_dpp v143, v141 quad_perm:[1,0,3,2] row_mask:0xf bank_mask:0xf
	v_lshl_add_u64 v[150:151], v[2:3], 1, s[60:61]
	v_lshl_add_u64 v[150:151], v[150:151], 0, v[134:135]
	v_perm_b32 v144, v142, v140, v136
	v_perm_b32 v145, v143, v141, v136
	s_nop 1
	v_mov_b32_dpp v146, v144 quad_perm:[2,3,0,1] row_mask:0xf bank_mask:0xf
	v_mov_b32_dpp v147, v145 quad_perm:[2,3,0,1] row_mask:0xf bank_mask:0xf
	s_nop 0
	v_cndmask_b32_e64 v148, v144, v147, s[44:45]
	v_cndmask_b32_e64 v149, v146, v145, s[44:45]
	global_store_dwordx2 v[150:151], v[148:149], off
	v_cvt_pk_bf16_f32 v156, v76, v77
	v_cvt_pk_bf16_f32 v157, v78, v79
	v_add_u32_e32 v168, 0xfffff000, v222
	v_lshrrev_b32_e32 v169, 8, v222
	v_ashrrev_i32_e32 v168, 10, v168
	v_cndmask_b32_e64 v169, v168, v169, s[40:41]
	v_and_b32_e32 v168, s82, v222
	v_lshl_add_u32 v169, v169, 9, v138
	v_or_b32_e32 v168, s65, v168
	v_lshl_add_u32 v2, v169, s68, v168
	v_mov_b32_dpp v158, v156 quad_perm:[1,0,3,2] row_mask:0xf bank_mask:0xf
	v_mov_b32_dpp v159, v157 quad_perm:[1,0,3,2] row_mask:0xf bank_mask:0xf
	v_lshl_add_u64 v[166:167], v[2:3], 1, s[60:61]
	v_lshl_add_u64 v[166:167], v[166:167], 0, v[134:135]
	v_perm_b32 v160, v158, v156, v136
	v_perm_b32 v161, v159, v157, v136
	s_nop 1
	v_mov_b32_dpp v162, v160 quad_perm:[2,3,0,1] row_mask:0xf bank_mask:0xf
	v_mov_b32_dpp v163, v161 quad_perm:[2,3,0,1] row_mask:0xf bank_mask:0xf
	s_nop 0
	v_cndmask_b32_e64 v164, v160, v163, s[44:45]
	v_cndmask_b32_e64 v165, v162, v161, s[44:45]
	global_store_dwordx2 v[166:167], v[164:165], off
	v_cvt_pk_bf16_f32 v140, v60, v61
	v_cvt_pk_bf16_f32 v141, v62, v63
	v_add_u32_e32 v152, 0xfffff000, v221
	v_lshrrev_b32_e32 v153, 8, v221
	v_ashrrev_i32_e32 v152, 10, v152
	v_cndmask_b32_e64 v153, v152, v153, s[40:41]
	v_and_b32_e32 v152, s82, v221
	v_lshl_add_u32 v153, v153, 9, v138
	v_or_b32_e32 v152, s65, v152
	v_lshl_add_u32 v2, v153, s68, v152
	v_mov_b32_dpp v142, v140 quad_perm:[1,0,3,2] row_mask:0xf bank_mask:0xf
	v_mov_b32_dpp v143, v141 quad_perm:[1,0,3,2] row_mask:0xf bank_mask:0xf
	v_lshl_add_u64 v[150:151], v[2:3], 1, s[60:61]
	v_lshl_add_u64 v[150:151], v[150:151], 0, v[134:135]
	v_perm_b32 v144, v142, v140, v136
	v_perm_b32 v145, v143, v141, v136
	s_nop 1
	v_mov_b32_dpp v146, v144 quad_perm:[2,3,0,1] row_mask:0xf bank_mask:0xf
	v_mov_b32_dpp v147, v145 quad_perm:[2,3,0,1] row_mask:0xf bank_mask:0xf
	s_nop 0
	v_cndmask_b32_e64 v148, v144, v147, s[44:45]
	v_cndmask_b32_e64 v149, v146, v145, s[44:45]
	global_store_dwordx2 v[150:151], v[148:149], off
	v_cvt_pk_bf16_f32 v156, v44, v45
	v_cvt_pk_bf16_f32 v157, v46, v47
	v_add_u32_e32 v168, 0xfffff000, v220
	v_lshrrev_b32_e32 v169, 8, v220
	v_ashrrev_i32_e32 v168, 10, v168
	v_cndmask_b32_e64 v169, v168, v169, s[40:41]
	v_and_b32_e32 v168, s82, v220
	v_lshl_add_u32 v169, v169, 9, v138
	v_or_b32_e32 v168, s65, v168
	v_lshl_add_u32 v2, v169, s68, v168
	v_mov_b32_dpp v158, v156 quad_perm:[1,0,3,2] row_mask:0xf bank_mask:0xf
	v_mov_b32_dpp v159, v157 quad_perm:[1,0,3,2] row_mask:0xf bank_mask:0xf
	v_lshl_add_u64 v[166:167], v[2:3], 1, s[60:61]
	v_lshl_add_u64 v[166:167], v[166:167], 0, v[134:135]
	v_perm_b32 v160, v158, v156, v136
	v_perm_b32 v161, v159, v157, v136
	s_nop 1
	v_mov_b32_dpp v162, v160 quad_perm:[2,3,0,1] row_mask:0xf bank_mask:0xf
	v_mov_b32_dpp v163, v161 quad_perm:[2,3,0,1] row_mask:0xf bank_mask:0xf
	s_nop 0
	v_cndmask_b32_e64 v164, v160, v163, s[44:45]
	v_cndmask_b32_e64 v165, v162, v161, s[44:45]
	global_store_dwordx2 v[166:167], v[164:165], off
	v_cvt_pk_bf16_f32 v140, v28, v29
	v_cvt_pk_bf16_f32 v141, v30, v31
	v_add_u32_e32 v152, 0xfffff000, v195
	v_lshrrev_b32_e32 v153, 8, v195
	v_ashrrev_i32_e32 v152, 10, v152
	v_cndmask_b32_e64 v153, v152, v153, s[40:41]
	v_and_b32_e32 v152, s82, v195
	v_lshl_add_u32 v153, v153, 9, v138
	v_or_b32_e32 v152, s65, v152
	v_lshl_add_u32 v2, v153, s68, v152
	v_mov_b32_dpp v142, v140 quad_perm:[1,0,3,2] row_mask:0xf bank_mask:0xf
	v_mov_b32_dpp v143, v141 quad_perm:[1,0,3,2] row_mask:0xf bank_mask:0xf
	v_lshl_add_u64 v[150:151], v[2:3], 1, s[60:61]
	v_lshl_add_u64 v[150:151], v[150:151], 0, v[134:135]
	v_perm_b32 v144, v142, v140, v136
	v_perm_b32 v145, v143, v141, v136
	s_nop 1
	v_mov_b32_dpp v146, v144 quad_perm:[2,3,0,1] row_mask:0xf bank_mask:0xf
	v_mov_b32_dpp v147, v145 quad_perm:[2,3,0,1] row_mask:0xf bank_mask:0xf
	s_nop 0
	v_cndmask_b32_e64 v148, v144, v147, s[44:45]
	v_cndmask_b32_e64 v149, v146, v145, s[44:45]
	global_store_dwordx2 v[150:151], v[148:149], off
	v_cvt_pk_bf16_f32 v156, v12, v13
	v_cvt_pk_bf16_f32 v157, v14, v15
	v_add_u32_e32 v168, 0xfffff000, v194
	v_lshrrev_b32_e32 v169, 8, v194
	v_ashrrev_i32_e32 v168, 10, v168
	v_cndmask_b32_e64 v169, v168, v169, s[40:41]
	v_and_b32_e32 v168, s82, v194
	v_lshl_add_u32 v169, v169, 9, v138
	v_or_b32_e32 v168, s65, v168
	v_lshl_add_u32 v2, v169, s68, v168
	v_mov_b32_dpp v158, v156 quad_perm:[1,0,3,2] row_mask:0xf bank_mask:0xf
	v_mov_b32_dpp v159, v157 quad_perm:[1,0,3,2] row_mask:0xf bank_mask:0xf
	v_lshl_add_u64 v[166:167], v[2:3], 1, s[60:61]
	v_lshl_add_u64 v[166:167], v[166:167], 0, v[134:135]
	v_perm_b32 v160, v158, v156, v136
	v_perm_b32 v161, v159, v157, v136
	s_nop 1
	v_mov_b32_dpp v162, v160 quad_perm:[2,3,0,1] row_mask:0xf bank_mask:0xf
	v_mov_b32_dpp v163, v161 quad_perm:[2,3,0,1] row_mask:0xf bank_mask:0xf
	s_nop 0
	v_cndmask_b32_e64 v164, v160, v163, s[44:45]
	v_cndmask_b32_e64 v165, v162, v161, s[44:45]
	global_store_dwordx2 v[166:167], v[164:165], off
	s_lshl_b32 s44, s62, 1
	s_mov_b32 s45, s21
	s_mov_b64 s[4:5], 0
	s_branch .LBB0_1285
.Lts_fast1:
	v_and_b32_e32 v132, 3, v202
	s_lshl_b32 s20, s64, 1
	s_add_i32 vcc_lo, s20, -2
	v_and_b32_e32 v133, 1, v132
	v_mul_lo_u32 v134, v132, vcc_lo
	v_mov_b32_e32 v135, 0
	v_cmp_eq_u32_e64 s[4:5], 1, v133
	v_and_b32_e32 v133, 2, v132
	v_mov_b32_e32 v136, 0x5040100
	v_mov_b32_e32 v137, 0x3020706
	v_cmp_eq_u32_e64 s[44:45], 2, v133
	s_nop 1
	v_cndmask_b32_e64 v136, v136, v137, s[4:5]
	v_add_u32_e32 v138, s80, v233
	v_cvt_pk_bf16_f32 v140, v120, v121
	v_cvt_pk_bf16_f32 v141, v122, v123
	v_add_u32_e32 v152, 0xfffff000, v225
	v_lshrrev_b32_e32 v153, 8, v225
	v_ashrrev_i32_e32 v152, 10, v152
	v_cndmask_b32_e64 v153, v152, v153, s[40:41]
	v_and_b32_e32 v152, s82, v225
	v_lshl_add_u32 v153, v153, 9, v138
	v_or_b32_e32 v152, s65, v152
	v_lshl_add_u32 v2, v153, s68, v152
	v_mov_b32_dpp v142, v140 quad_perm:[1,0,3,2] row_mask:0xf bank_mask:0xf
	v_mov_b32_dpp v143, v141 quad_perm:[1,0,3,2] row_mask:0xf bank_mask:0xf
	v_lshl_add_u64 v[150:151], v[2:3], 1, s[60:61]
	v_lshl_add_u64 v[150:151], v[150:151], 0, v[134:135]
	v_perm_b32 v144, v142, v140, v136
	v_perm_b32 v145, v143, v141, v136
	s_nop 1
	v_mov_b32_dpp v146, v144 quad_perm:[2,3,0,1] row_mask:0xf bank_mask:0xf
	v_mov_b32_dpp v147, v145 quad_perm:[2,3,0,1] row_mask:0xf bank_mask:0xf
	s_nop 0
	v_cndmask_b32_e64 v148, v144, v147, s[44:45]
	v_cndmask_b32_e64 v149, v146, v145, s[44:45]
	global_store_dwordx2 v[150:151], v[148:149], off
	v_cvt_pk_bf16_f32 v156, v104, v105
	v_cvt_pk_bf16_f32 v157, v106, v107
	v_add_u32_e32 v168, 0xfffff000, v224
	v_lshrrev_b32_e32 v169, 8, v224
	v_ashrrev_i32_e32 v168, 10, v168
	v_cndmask_b32_e64 v169, v168, v169, s[40:41]
	v_and_b32_e32 v168, s82, v224
	v_lshl_add_u32 v169, v169, 9, v138
	v_or_b32_e32 v168, s65, v168
	v_lshl_add_u32 v2, v169, s68, v168
	v_mov_b32_dpp v158, v156 quad_perm:[1,0,3,2] row_mask:0xf bank_mask:0xf
	v_mov_b32_dpp v159, v157 quad_perm:[1,0,3,2] row_mask:0xf bank_mask:0xf
	v_lshl_add_u64 v[166:167], v[2:3], 1, s[60:61]
	v_lshl_add_u64 v[166:167], v[166:167], 0, v[134:135]
	v_perm_b32 v160, v158, v156, v136
	v_perm_b32 v161, v159, v157, v136
	s_nop 1
	v_mov_b32_dpp v162, v160 quad_perm:[2,3,0,1] row_mask:0xf bank_mask:0xf
	v_mov_b32_dpp v163, v161 quad_perm:[2,3,0,1] row_mask:0xf bank_mask:0xf
	s_nop 0
	v_cndmask_b32_e64 v164, v160, v163, s[44:45]
	v_cndmask_b32_e64 v165, v162, v161, s[44:45]
	global_store_dwordx2 v[166:167], v[164:165], off
	v_cvt_pk_bf16_f32 v140, v88, v89
	v_cvt_pk_bf16_f32 v141, v90, v91
	v_add_u32_e32 v152, 0xfffff000, v223
	v_lshrrev_b32_e32 v153, 8, v223
	v_ashrrev_i32_e32 v152, 10, v152
	v_cndmask_b32_e64 v153, v152, v153, s[40:41]
	v_and_b32_e32 v152, s82, v223
	v_lshl_add_u32 v153, v153, 9, v138
	v_or_b32_e32 v152, s65, v152
	v_lshl_add_u32 v2, v153, s68, v152
	v_mov_b32_dpp v142, v140 quad_perm:[1,0,3,2] row_mask:0xf bank_mask:0xf
	v_mov_b32_dpp v143, v141 quad_perm:[1,0,3,2] row_mask:0xf bank_mask:0xf
	v_lshl_add_u64 v[150:151], v[2:3], 1, s[60:61]
	v_lshl_add_u64 v[150:151], v[150:151], 0, v[134:135]
	v_perm_b32 v144, v142, v140, v136
	v_perm_b32 v145, v143, v141, v136
	s_nop 1
	v_mov_b32_dpp v146, v144 quad_perm:[2,3,0,1] row_mask:0xf bank_mask:0xf
	v_mov_b32_dpp v147, v145 quad_perm:[2,3,0,1] row_mask:0xf bank_mask:0xf
	s_nop 0
	v_cndmask_b32_e64 v148, v144, v147, s[44:45]
	v_cndmask_b32_e64 v149, v146, v145, s[44:45]
	global_store_dwordx2 v[150:151], v[148:149], off
	v_cvt_pk_bf16_f32 v156, v72, v73
	v_cvt_pk_bf16_f32 v157, v74, v75
	v_add_u32_e32 v168, 0xfffff000, v222
	v_lshrrev_b32_e32 v169, 8, v222
	v_ashrrev_i32_e32 v168, 10, v168
	v_cndmask_b32_e64 v169, v168, v169, s[40:41]
	v_and_b32_e32 v168, s82, v222
	v_lshl_add_u32 v169, v169, 9, v138
	v_or_b32_e32 v168, s65, v168
	v_lshl_add_u32 v2, v169, s68, v168
	v_mov_b32_dpp v158, v156 quad_perm:[1,0,3,2] row_mask:0xf bank_mask:0xf
	v_mov_b32_dpp v159, v157 quad_perm:[1,0,3,2] row_mask:0xf bank_mask:0xf
	v_lshl_add_u64 v[166:167], v[2:3], 1, s[60:61]
	v_lshl_add_u64 v[166:167], v[166:167], 0, v[134:135]
	v_perm_b32 v160, v158, v156, v136
	v_perm_b32 v161, v159, v157, v136
	s_nop 1
	v_mov_b32_dpp v162, v160 quad_perm:[2,3,0,1] row_mask:0xf bank_mask:0xf
	v_mov_b32_dpp v163, v161 quad_perm:[2,3,0,1] row_mask:0xf bank_mask:0xf
	s_nop 0
	v_cndmask_b32_e64 v164, v160, v163, s[44:45]
	v_cndmask_b32_e64 v165, v162, v161, s[44:45]
	global_store_dwordx2 v[166:167], v[164:165], off
	v_cvt_pk_bf16_f32 v140, v56, v57
	v_cvt_pk_bf16_f32 v141, v58, v59
	v_add_u32_e32 v152, 0xfffff000, v221
	v_lshrrev_b32_e32 v153, 8, v221
	v_ashrrev_i32_e32 v152, 10, v152
	v_cndmask_b32_e64 v153, v152, v153, s[40:41]
	v_and_b32_e32 v152, s82, v221
	v_lshl_add_u32 v153, v153, 9, v138
	v_or_b32_e32 v152, s65, v152
	v_lshl_add_u32 v2, v153, s68, v152
	v_mov_b32_dpp v142, v140 quad_perm:[1,0,3,2] row_mask:0xf bank_mask:0xf
	v_mov_b32_dpp v143, v141 quad_perm:[1,0,3,2] row_mask:0xf bank_mask:0xf
	v_lshl_add_u64 v[150:151], v[2:3], 1, s[60:61]
	v_lshl_add_u64 v[150:151], v[150:151], 0, v[134:135]
	v_perm_b32 v144, v142, v140, v136
	v_perm_b32 v145, v143, v141, v136
	s_nop 1
	v_mov_b32_dpp v146, v144 quad_perm:[2,3,0,1] row_mask:0xf bank_mask:0xf
	v_mov_b32_dpp v147, v145 quad_perm:[2,3,0,1] row_mask:0xf bank_mask:0xf
	s_nop 0
	v_cndmask_b32_e64 v148, v144, v147, s[44:45]
	v_cndmask_b32_e64 v149, v146, v145, s[44:45]
	global_store_dwordx2 v[150:151], v[148:149], off
	v_cvt_pk_bf16_f32 v156, v40, v41
	v_cvt_pk_bf16_f32 v157, v42, v43
	v_add_u32_e32 v168, 0xfffff000, v220
	v_lshrrev_b32_e32 v169, 8, v220
	v_ashrrev_i32_e32 v168, 10, v168
	v_cndmask_b32_e64 v169, v168, v169, s[40:41]
	v_and_b32_e32 v168, s82, v220
	v_lshl_add_u32 v169, v169, 9, v138
	v_or_b32_e32 v168, s65, v168
	v_lshl_add_u32 v2, v169, s68, v168
	v_mov_b32_dpp v158, v156 quad_perm:[1,0,3,2] row_mask:0xf bank_mask:0xf
	v_mov_b32_dpp v159, v157 quad_perm:[1,0,3,2] row_mask:0xf bank_mask:0xf
	v_lshl_add_u64 v[166:167], v[2:3], 1, s[60:61]
	v_lshl_add_u64 v[166:167], v[166:167], 0, v[134:135]
	v_perm_b32 v160, v158, v156, v136
	v_perm_b32 v161, v159, v157, v136
	s_nop 1
	v_mov_b32_dpp v162, v160 quad_perm:[2,3,0,1] row_mask:0xf bank_mask:0xf
	v_mov_b32_dpp v163, v161 quad_perm:[2,3,0,1] row_mask:0xf bank_mask:0xf
	s_nop 0
	v_cndmask_b32_e64 v164, v160, v163, s[44:45]
	v_cndmask_b32_e64 v165, v162, v161, s[44:45]
	global_store_dwordx2 v[166:167], v[164:165], off
	v_cvt_pk_bf16_f32 v140, v24, v25
	v_cvt_pk_bf16_f32 v141, v26, v27
	v_add_u32_e32 v152, 0xfffff000, v195
	v_lshrrev_b32_e32 v153, 8, v195
	v_ashrrev_i32_e32 v152, 10, v152
	v_cndmask_b32_e64 v153, v152, v153, s[40:41]
	v_and_b32_e32 v152, s82, v195
	v_lshl_add_u32 v153, v153, 9, v138
	v_or_b32_e32 v152, s65, v152
	v_lshl_add_u32 v2, v153, s68, v152
	v_mov_b32_dpp v142, v140 quad_perm:[1,0,3,2] row_mask:0xf bank_mask:0xf
	v_mov_b32_dpp v143, v141 quad_perm:[1,0,3,2] row_mask:0xf bank_mask:0xf
	v_lshl_add_u64 v[150:151], v[2:3], 1, s[60:61]
	v_lshl_add_u64 v[150:151], v[150:151], 0, v[134:135]
	v_perm_b32 v144, v142, v140, v136
	v_perm_b32 v145, v143, v141, v136
	s_nop 1
	v_mov_b32_dpp v146, v144 quad_perm:[2,3,0,1] row_mask:0xf bank_mask:0xf
	v_mov_b32_dpp v147, v145 quad_perm:[2,3,0,1] row_mask:0xf bank_mask:0xf
	s_nop 0
	v_cndmask_b32_e64 v148, v144, v147, s[44:45]
	v_cndmask_b32_e64 v149, v146, v145, s[44:45]
	global_store_dwordx2 v[150:151], v[148:149], off
	v_cvt_pk_bf16_f32 v156, v8, v9
	v_cvt_pk_bf16_f32 v157, v10, v11
	v_add_u32_e32 v168, 0xfffff000, v194
	v_lshrrev_b32_e32 v169, 8, v194
	v_ashrrev_i32_e32 v168, 10, v168
	v_cndmask_b32_e64 v169, v168, v169, s[40:41]
	v_and_b32_e32 v168, s82, v194
	v_lshl_add_u32 v169, v169, 9, v138
	v_or_b32_e32 v168, s65, v168
	v_lshl_add_u32 v2, v169, s68, v168
	v_mov_b32_dpp v158, v156 quad_perm:[1,0,3,2] row_mask:0xf bank_mask:0xf
	v_mov_b32_dpp v159, v157 quad_perm:[1,0,3,2] row_mask:0xf bank_mask:0xf
	v_lshl_add_u64 v[166:167], v[2:3], 1, s[60:61]
	v_lshl_add_u64 v[166:167], v[166:167], 0, v[134:135]
	v_perm_b32 v160, v158, v156, v136
	v_perm_b32 v161, v159, v157, v136
	s_nop 1
	v_mov_b32_dpp v162, v160 quad_perm:[2,3,0,1] row_mask:0xf bank_mask:0xf
	v_mov_b32_dpp v163, v161 quad_perm:[2,3,0,1] row_mask:0xf bank_mask:0xf
	s_nop 0
	v_cndmask_b32_e64 v164, v160, v163, s[44:45]
	v_cndmask_b32_e64 v165, v162, v161, s[44:45]
	global_store_dwordx2 v[166:167], v[164:165], off
	v_add_u32_e32 v138, s80, v233
	v_add_u32_e32 v138, 16, v138
	v_cvt_pk_bf16_f32 v140, v116, v117
	v_cvt_pk_bf16_f32 v141, v118, v119
	v_add_u32_e32 v152, 0xfffff000, v225
	v_lshrrev_b32_e32 v153, 8, v225
	v_ashrrev_i32_e32 v152, 10, v152
	v_cndmask_b32_e64 v153, v152, v153, s[40:41]
	v_and_b32_e32 v152, s82, v225
	v_lshl_add_u32 v153, v153, 9, v138
	v_or_b32_e32 v152, s65, v152
	v_lshl_add_u32 v2, v153, s68, v152
	v_mov_b32_dpp v142, v140 quad_perm:[1,0,3,2] row_mask:0xf bank_mask:0xf
	v_mov_b32_dpp v143, v141 quad_perm:[1,0,3,2] row_mask:0xf bank_mask:0xf
	v_lshl_add_u64 v[150:151], v[2:3], 1, s[60:61]
	v_lshl_add_u64 v[150:151], v[150:151], 0, v[134:135]
	v_perm_b32 v144, v142, v140, v136
	v_perm_b32 v145, v143, v141, v136
	s_nop 1
	v_mov_b32_dpp v146, v144 quad_perm:[2,3,0,1] row_mask:0xf bank_mask:0xf
	v_mov_b32_dpp v147, v145 quad_perm:[2,3,0,1] row_mask:0xf bank_mask:0xf
	s_nop 0
	v_cndmask_b32_e64 v148, v144, v147, s[44:45]
	v_cndmask_b32_e64 v149, v146, v145, s[44:45]
	global_store_dwordx2 v[150:151], v[148:149], off
	v_cvt_pk_bf16_f32 v156, v100, v101
	v_cvt_pk_bf16_f32 v157, v102, v103
	v_add_u32_e32 v168, 0xfffff000, v224
	v_lshrrev_b32_e32 v169, 8, v224
	v_ashrrev_i32_e32 v168, 10, v168
	v_cndmask_b32_e64 v169, v168, v169, s[40:41]
	v_and_b32_e32 v168, s82, v224
	v_lshl_add_u32 v169, v169, 9, v138
	v_or_b32_e32 v168, s65, v168
	v_lshl_add_u32 v2, v169, s68, v168
	v_mov_b32_dpp v158, v156 quad_perm:[1,0,3,2] row_mask:0xf bank_mask:0xf
	v_mov_b32_dpp v159, v157 quad_perm:[1,0,3,2] row_mask:0xf bank_mask:0xf
	v_lshl_add_u64 v[166:167], v[2:3], 1, s[60:61]
	v_lshl_add_u64 v[166:167], v[166:167], 0, v[134:135]
	v_perm_b32 v160, v158, v156, v136
	v_perm_b32 v161, v159, v157, v136
	s_nop 1
	v_mov_b32_dpp v162, v160 quad_perm:[2,3,0,1] row_mask:0xf bank_mask:0xf
	v_mov_b32_dpp v163, v161 quad_perm:[2,3,0,1] row_mask:0xf bank_mask:0xf
	s_nop 0
	v_cndmask_b32_e64 v164, v160, v163, s[44:45]
	v_cndmask_b32_e64 v165, v162, v161, s[44:45]
	global_store_dwordx2 v[166:167], v[164:165], off
	v_cvt_pk_bf16_f32 v140, v84, v85
	v_cvt_pk_bf16_f32 v141, v86, v87
	v_add_u32_e32 v152, 0xfffff000, v223
	v_lshrrev_b32_e32 v153, 8, v223
	v_ashrrev_i32_e32 v152, 10, v152
	v_cndmask_b32_e64 v153, v152, v153, s[40:41]
	v_and_b32_e32 v152, s82, v223
	v_lshl_add_u32 v153, v153, 9, v138
	v_or_b32_e32 v152, s65, v152
	v_lshl_add_u32 v2, v153, s68, v152
	v_mov_b32_dpp v142, v140 quad_perm:[1,0,3,2] row_mask:0xf bank_mask:0xf
	v_mov_b32_dpp v143, v141 quad_perm:[1,0,3,2] row_mask:0xf bank_mask:0xf
	v_lshl_add_u64 v[150:151], v[2:3], 1, s[60:61]
	v_lshl_add_u64 v[150:151], v[150:151], 0, v[134:135]
	v_perm_b32 v144, v142, v140, v136
	v_perm_b32 v145, v143, v141, v136
	s_nop 1
	v_mov_b32_dpp v146, v144 quad_perm:[2,3,0,1] row_mask:0xf bank_mask:0xf
	v_mov_b32_dpp v147, v145 quad_perm:[2,3,0,1] row_mask:0xf bank_mask:0xf
	s_nop 0
	v_cndmask_b32_e64 v148, v144, v147, s[44:45]
	v_cndmask_b32_e64 v149, v146, v145, s[44:45]
	global_store_dwordx2 v[150:151], v[148:149], off
	v_cvt_pk_bf16_f32 v156, v68, v69
	v_cvt_pk_bf16_f32 v157, v70, v71
	v_add_u32_e32 v168, 0xfffff000, v222
	v_lshrrev_b32_e32 v169, 8, v222
	v_ashrrev_i32_e32 v168, 10, v168
	v_cndmask_b32_e64 v169, v168, v169, s[40:41]
	v_and_b32_e32 v168, s82, v222
	v_lshl_add_u32 v169, v169, 9, v138
	v_or_b32_e32 v168, s65, v168
	v_lshl_add_u32 v2, v169, s68, v168
	v_mov_b32_dpp v158, v156 quad_perm:[1,0,3,2] row_mask:0xf bank_mask:0xf
	v_mov_b32_dpp v159, v157 quad_perm:[1,0,3,2] row_mask:0xf bank_mask:0xf
	v_lshl_add_u64 v[166:167], v[2:3], 1, s[60:61]
	v_lshl_add_u64 v[166:167], v[166:167], 0, v[134:135]
	v_perm_b32 v160, v158, v156, v136
	v_perm_b32 v161, v159, v157, v136
	s_nop 1
	v_mov_b32_dpp v162, v160 quad_perm:[2,3,0,1] row_mask:0xf bank_mask:0xf
	v_mov_b32_dpp v163, v161 quad_perm:[2,3,0,1] row_mask:0xf bank_mask:0xf
	s_nop 0
	v_cndmask_b32_e64 v164, v160, v163, s[44:45]
	v_cndmask_b32_e64 v165, v162, v161, s[44:45]
	global_store_dwordx2 v[166:167], v[164:165], off
	v_cvt_pk_bf16_f32 v140, v52, v53
	v_cvt_pk_bf16_f32 v141, v54, v55
	v_add_u32_e32 v152, 0xfffff000, v221
	v_lshrrev_b32_e32 v153, 8, v221
	v_ashrrev_i32_e32 v152, 10, v152
	v_cndmask_b32_e64 v153, v152, v153, s[40:41]
	v_and_b32_e32 v152, s82, v221
	v_lshl_add_u32 v153, v153, 9, v138
	v_or_b32_e32 v152, s65, v152
	v_lshl_add_u32 v2, v153, s68, v152
	v_mov_b32_dpp v142, v140 quad_perm:[1,0,3,2] row_mask:0xf bank_mask:0xf
	v_mov_b32_dpp v143, v141 quad_perm:[1,0,3,2] row_mask:0xf bank_mask:0xf
	v_lshl_add_u64 v[150:151], v[2:3], 1, s[60:61]
	v_lshl_add_u64 v[150:151], v[150:151], 0, v[134:135]
	v_perm_b32 v144, v142, v140, v136
	v_perm_b32 v145, v143, v141, v136
	s_nop 1
	v_mov_b32_dpp v146, v144 quad_perm:[2,3,0,1] row_mask:0xf bank_mask:0xf
	v_mov_b32_dpp v147, v145 quad_perm:[2,3,0,1] row_mask:0xf bank_mask:0xf
	s_nop 0
	v_cndmask_b32_e64 v148, v144, v147, s[44:45]
	v_cndmask_b32_e64 v149, v146, v145, s[44:45]
	global_store_dwordx2 v[150:151], v[148:149], off
	v_cvt_pk_bf16_f32 v156, v36, v37
	v_cvt_pk_bf16_f32 v157, v38, v39
	v_add_u32_e32 v168, 0xfffff000, v220
	v_lshrrev_b32_e32 v169, 8, v220
	v_ashrrev_i32_e32 v168, 10, v168
	v_cndmask_b32_e64 v169, v168, v169, s[40:41]
	v_and_b32_e32 v168, s82, v220
	v_lshl_add_u32 v169, v169, 9, v138
	v_or_b32_e32 v168, s65, v168
	v_lshl_add_u32 v2, v169, s68, v168
	v_mov_b32_dpp v158, v156 quad_perm:[1,0,3,2] row_mask:0xf bank_mask:0xf
	v_mov_b32_dpp v159, v157 quad_perm:[1,0,3,2] row_mask:0xf bank_mask:0xf
	v_lshl_add_u64 v[166:167], v[2:3], 1, s[60:61]
	v_lshl_add_u64 v[166:167], v[166:167], 0, v[134:135]
	v_perm_b32 v160, v158, v156, v136
	v_perm_b32 v161, v159, v157, v136
	s_nop 1
	v_mov_b32_dpp v162, v160 quad_perm:[2,3,0,1] row_mask:0xf bank_mask:0xf
	v_mov_b32_dpp v163, v161 quad_perm:[2,3,0,1] row_mask:0xf bank_mask:0xf
	s_nop 0
	v_cndmask_b32_e64 v164, v160, v163, s[44:45]
	v_cndmask_b32_e64 v165, v162, v161, s[44:45]
	global_store_dwordx2 v[166:167], v[164:165], off
	v_cvt_pk_bf16_f32 v140, v20, v21
	v_cvt_pk_bf16_f32 v141, v22, v23
	v_add_u32_e32 v152, 0xfffff000, v195
	v_lshrrev_b32_e32 v153, 8, v195
	v_ashrrev_i32_e32 v152, 10, v152
	v_cndmask_b32_e64 v153, v152, v153, s[40:41]
	v_and_b32_e32 v152, s82, v195
	v_lshl_add_u32 v153, v153, 9, v138
	v_or_b32_e32 v152, s65, v152
	v_lshl_add_u32 v2, v153, s68, v152
	v_mov_b32_dpp v142, v140 quad_perm:[1,0,3,2] row_mask:0xf bank_mask:0xf
	v_mov_b32_dpp v143, v141 quad_perm:[1,0,3,2] row_mask:0xf bank_mask:0xf
	v_lshl_add_u64 v[150:151], v[2:3], 1, s[60:61]
	v_lshl_add_u64 v[150:151], v[150:151], 0, v[134:135]
	v_perm_b32 v144, v142, v140, v136
	v_perm_b32 v145, v143, v141, v136
	s_nop 1
	v_mov_b32_dpp v146, v144 quad_perm:[2,3,0,1] row_mask:0xf bank_mask:0xf
	v_mov_b32_dpp v147, v145 quad_perm:[2,3,0,1] row_mask:0xf bank_mask:0xf
	s_nop 0
	v_cndmask_b32_e64 v148, v144, v147, s[44:45]
	v_cndmask_b32_e64 v149, v146, v145, s[44:45]
	global_store_dwordx2 v[150:151], v[148:149], off
	v_cvt_pk_bf16_f32 v156, v4, v5
	v_cvt_pk_bf16_f32 v157, v6, v7
	v_add_u32_e32 v168, 0xfffff000, v194
	v_lshrrev_b32_e32 v169, 8, v194
	v_ashrrev_i32_e32 v168, 10, v168
	v_cndmask_b32_e64 v169, v168, v169, s[40:41]
	v_and_b32_e32 v168, s82, v194
	v_lshl_add_u32 v169, v169, 9, v138
	v_or_b32_e32 v168, s65, v168
	v_lshl_add_u32 v2, v169, s68, v168
	v_mov_b32_dpp v158, v156 quad_perm:[1,0,3,2] row_mask:0xf bank_mask:0xf
	v_mov_b32_dpp v159, v157 quad_perm:[1,0,3,2] row_mask:0xf bank_mask:0xf
	v_lshl_add_u64 v[166:167], v[2:3], 1, s[60:61]
	v_lshl_add_u64 v[166:167], v[166:167], 0, v[134:135]
	v_perm_b32 v160, v158, v156, v136
	v_perm_b32 v161, v159, v157, v136
	s_nop 1
	v_mov_b32_dpp v162, v160 quad_perm:[2,3,0,1] row_mask:0xf bank_mask:0xf
	v_mov_b32_dpp v163, v161 quad_perm:[2,3,0,1] row_mask:0xf bank_mask:0xf
	s_nop 0
	v_cndmask_b32_e64 v164, v160, v163, s[44:45]
	v_cndmask_b32_e64 v165, v162, v161, s[44:45]
	global_store_dwordx2 v[166:167], v[164:165], off
	s_lshl_b32 s44, s62, 1
	s_mov_b32 s45, s21
	s_mov_b64 s[4:5], 0
	s_branch .LBB0_1396
